# baseline (speedup 1.0000x reference)
; __device__ __forceinline__ void gmlp_item(PARAMS_T& p, int l, int b, int pos0, int tokrow0) {
;     ...
;   {
;     const int dim = tid >> 1, half = tid & 1;
;     const float gd = p.gm_v_g[l * 256 + dim];
;     const unsigned short* src = (const unsigned short*)(p.ws + OFF_VT) + ((size_t)b * 256 + dim) * PTOK + pos0 + half * 64;
; #pragma unroll
;     for (int i = 0; i < 8; ++i) {
;       u32x4 w = *reinterpret_cast<const u32x4*>(src + i * 8);
;       const int t0 = half * 64 + i * 8;
;       float f0 = __uint_as_float(w[0] << 16) * rs[t0 + 0] * gd, f1 = __uint_as_float(w[0] & 0xffff0000u) * rs[t0 + 1] * gd;
;       float f2 = __uint_as_float(w[1] << 16) * rs[t0 + 2] * gd, f3 = __uint_as_float(w[1] & 0xffff0000u) * rs[t0 + 3] * gd;
;       float f4 = __uint_as_float(w[2] << 16) * rs[t0 + 4] * gd, f5 = __uint_as_float(w[2] & 0xffff0000u) * rs[t0 + 5] * gd;
;       float f6 = __uint_as_float(w[3] << 16) * rs[t0 + 6] * gd, f7 = __uint_as_float(w[3] & 0xffff0000u) * rs[t0 + 7] * gd;
;       u32x4 o = {cvtpk(f0, f1), cvtpk(f2, f3), cvtpk(f4, f5), cvtpk(f6, f7)};
;       *reinterpret_cast<u32x4*>(Vn + dim * 136 + t0) = o;
;     }
;   }
.LBB0_825:
	s_or_b64 exec, exec, s[6:7]
	s_or_b32 s6, s9, 0x2000
	s_and_b64 s[4:5], s[4:5], exec
	v_ashrrev_i32_e32 v34, 1, v20
	s_cselect_b32 s6, s9, s6
	v_ashrrev_i32_e32 v35, 31, v34
	s_lshl_b64 s[4:5], s[88:89], 8
	v_lshl_add_u64 v[18:19], s[4:5], 0, v[34:35]
	v_readlane_b32 s4, v255, 34
	v_readlane_b32 s5, v255, 35
	s_movk_i32 s7, 0x4200
	v_lshlrev_b32_e32 v16, 6, v20
	v_mov_b64_e32 v[22:23], s[4:5]
	v_mad_u64_u32 v[22:23], s[4:5], v18, s7, v[22:23]
	v_mad_i32_i24 v23, v19, s7, v23
	s_lshl_b32 s88, s6, 1
	v_and_b32_e32 v21, 64, v16
	v_lshl_add_u64 v[18:19], v[22:23], 0, s[88:89]
	v_lshlrev_b32_e32 v16, 1, v21
	v_lshl_add_u64 v[18:19], v[18:19], 0, v[16:17]
	s_waitcnt lgkmcnt(0)
	s_barrier
	global_load_dwordx4 v[22:25], v[18:19], off
	s_load_dwordx2 s[6:7], s[86:87], 0x58
	s_load_dwordx2 s[4:5], s[86:87], 0x68
	v_lshl_add_u32 v36, v21, 2, 0
	v_ashrrev_i32_e32 v70, 7, v20
	v_ashrrev_i32_e32 v71, 31, v70
	s_waitcnt lgkmcnt(0)
	v_lshl_add_u64 v[26:27], v[34:35], 2, s[6:7]
	global_load_dword v35, v[26:27], off
	ds_read_b128 v[26:29], v36
	ds_read_b128 v[30:33], v36 offset:16
	s_movk_i32 s6, 0x110
	v_readlane_b32 s10, v255, 36
	v_bfe_u32 v73, v20, 5, 1
	v_bfe_u32 v76, v20, 6, 1
	v_readlane_b32 s11, v255, 37
	v_mov_b32_e32 v79, v17
	s_waitcnt vmcnt(1)
	v_lshlrev_b32_e32 v21, 16, v22
	v_and_b32_e32 v22, 0xffff0000, v22
	v_lshlrev_b32_e32 v37, 16, v23
	v_and_b32_e32 v23, 0xffff0000, v23
	v_lshlrev_b32_e32 v38, 16, v24
	v_and_b32_e32 v24, 0xffff0000, v24
	v_lshlrev_b32_e32 v39, 16, v25
	v_and_b32_e32 v25, 0xffff0000, v25
	s_waitcnt lgkmcnt(1)
	v_mul_f32_e32 v21, v26, v21
	v_mul_f32_e32 v22, v27, v22
	v_mul_f32_e32 v26, v28, v37
	v_mul_f32_e32 v23, v29, v23
	s_waitcnt lgkmcnt(0)
	v_mul_f32_e32 v27, v30, v38
	v_mul_f32_e32 v24, v31, v24
	v_mul_f32_e32 v28, v32, v39
	v_mul_f32_e32 v25, v33, v25
	s_waitcnt vmcnt(0)
	v_mul_f32_e32 v22, v35, v22
	v_mul_f32_e32 v26, v35, v26
	v_mul_f32_e32 v23, v35, v23
	v_mul_f32_e32 v27, v35, v27
	v_mul_f32_e32 v24, v35, v24
	v_mul_f32_e32 v28, v35, v28
	v_mul_f32_e32 v25, v35, v25
	v_mul_f32_e32 v21, v35, v21
	v_cvt_pk_bf16_f32 v22, v21, v22
	v_cvt_pk_bf16_f32 v23, v26, v23
	v_cvt_pk_bf16_f32 v24, v27, v24
	v_cvt_pk_bf16_f32 v25, v28, v25
	global_load_dwordx4 v[26:29], v[18:19], off offset:16
	v_mul_lo_u32 v21, v34, s6
	v_add3_u32 v34, 0, v21, v16
	ds_write_b128 v34, v[22:25] offset:1024
	ds_read_b128 v[22:25], v36 offset:32
	ds_read_b128 v[30:33], v36 offset:48
	s_waitcnt vmcnt(0)
	v_lshlrev_b32_e32 v16, 16, v26
	v_and_b32_e32 v21, 0xffff0000, v26
	v_lshlrev_b32_e32 v26, 16, v27
	v_and_b32_e32 v27, 0xffff0000, v27
	v_lshlrev_b32_e32 v37, 16, v28
	v_and_b32_e32 v28, 0xffff0000, v28
	v_lshlrev_b32_e32 v38, 16, v29
	v_and_b32_e32 v29, 0xffff0000, v29
	s_waitcnt lgkmcnt(1)
	v_mul_f32_e32 v16, v22, v16
	v_mul_f32_e32 v21, v23, v21
	v_mul_f32_e32 v22, v24, v26
	v_mul_f32_e32 v23, v25, v27
	s_waitcnt lgkmcnt(0)
	v_mul_f32_e32 v24, v30, v37
	v_mul_f32_e32 v25, v31, v28
	v_mul_f32_e32 v26, v32, v38
	v_mul_f32_e32 v27, v33, v29
	v_mul_f32_e32 v28, v35, v22
	v_mul_f32_e32 v23, v35, v23
	v_mul_f32_e32 v24, v35, v24
	v_mul_f32_e32 v25, v35, v25
	v_mul_f32_e32 v26, v35, v26
	v_mul_f32_e32 v27, v35, v27
	v_mul_f32_e32 v16, v35, v16
	v_mul_f32_e32 v21, v35, v21
	v_cvt_pk_bf16_f32 v22, v16, v21
	v_cvt_pk_bf16_f32 v23, v28, v23
	v_cvt_pk_bf16_f32 v24, v24, v25
	v_cvt_pk_bf16_f32 v25, v26, v27
	global_load_dwordx4 v[26:29], v[18:19], off offset:32
	ds_write_b128 v34, v[22:25] offset:1040
	ds_read_b128 v[22:25], v36 offset:64
	ds_read_b128 v[30:33], v36 offset:80
	s_waitcnt vmcnt(0)
	v_lshlrev_b32_e32 v16, 16, v26
	v_and_b32_e32 v21, 0xffff0000, v26
	v_lshlrev_b32_e32 v26, 16, v27
	v_and_b32_e32 v27, 0xffff0000, v27
	v_lshlrev_b32_e32 v37, 16, v28
	v_and_b32_e32 v28, 0xffff0000, v28
	v_lshlrev_b32_e32 v38, 16, v29
	v_and_b32_e32 v29, 0xffff0000, v29
	s_waitcnt lgkmcnt(1)
	v_mul_f32_e32 v16, v22, v16
	v_mul_f32_e32 v21, v23, v21
	v_mul_f32_e32 v22, v24, v26
	v_mul_f32_e32 v23, v25, v27
	s_waitcnt lgkmcnt(0)
	v_mul_f32_e32 v24, v30, v37
	v_mul_f32_e32 v25, v31, v28
	v_mul_f32_e32 v26, v32, v38
	v_mul_f32_e32 v27, v33, v29
	v_mul_f32_e32 v28, v35, v22
	v_mul_f32_e32 v23, v35, v23
	v_mul_f32_e32 v24, v35, v24
	v_mul_f32_e32 v25, v35, v25
	v_mul_f32_e32 v26, v35, v26
	v_mul_f32_e32 v27, v35, v27
	v_mul_f32_e32 v16, v35, v16
	v_mul_f32_e32 v21, v35, v21
	v_cvt_pk_bf16_f32 v22, v16, v21
	v_cvt_pk_bf16_f32 v23, v28, v23
	v_cvt_pk_bf16_f32 v24, v24, v25
	v_cvt_pk_bf16_f32 v25, v26, v27
	global_load_dwordx4 v[26:29], v[18:19], off offset:48
	ds_write_b128 v34, v[22:25] offset:1056
	ds_read_b128 v[22:25], v36 offset:96
	ds_read_b128 v[30:33], v36 offset:112
	s_waitcnt vmcnt(0)
	v_lshlrev_b32_e32 v16, 16, v26
	v_and_b32_e32 v21, 0xffff0000, v26
	v_lshlrev_b32_e32 v26, 16, v27
	v_and_b32_e32 v27, 0xffff0000, v27
	v_lshlrev_b32_e32 v37, 16, v28
	v_and_b32_e32 v28, 0xffff0000, v28
	v_lshlrev_b32_e32 v38, 16, v29
	v_and_b32_e32 v29, 0xffff0000, v29
	s_waitcnt lgkmcnt(1)
	v_mul_f32_e32 v16, v22, v16
	v_mul_f32_e32 v21, v23, v21
	v_mul_f32_e32 v22, v24, v26
	v_mul_f32_e32 v23, v25, v27
	s_waitcnt lgkmcnt(0)
	v_mul_f32_e32 v24, v30, v37
	v_mul_f32_e32 v25, v31, v28
	v_mul_f32_e32 v26, v32, v38
	v_mul_f32_e32 v27, v33, v29
	v_mul_f32_e32 v28, v35, v22
	v_mul_f32_e32 v23, v35, v23
	v_mul_f32_e32 v24, v35, v24
	v_mul_f32_e32 v25, v35, v25
	v_mul_f32_e32 v26, v35, v26
	v_mul_f32_e32 v27, v35, v27
	v_mul_f32_e32 v16, v35, v16
	v_mul_f32_e32 v21, v35, v21
	v_cvt_pk_bf16_f32 v22, v16, v21
	v_cvt_pk_bf16_f32 v23, v28, v23
	v_cvt_pk_bf16_f32 v24, v24, v25
	v_cvt_pk_bf16_f32 v25, v26, v27
	global_load_dwordx4 v[26:29], v[18:19], off offset:64
	ds_write_b128 v34, v[22:25] offset:1072
	ds_read_b128 v[22:25], v36 offset:128
	ds_read_b128 v[30:33], v36 offset:144
	s_waitcnt vmcnt(0)
; __device__ __forceinline__ void gmlp_item(PARAMS_T& p, int l, int b, int pos0, int tokrow0) {
;     ...
;     for (int i = 0; i < 8; ++i) {
;       u32x4 w = *reinterpret_cast<const u32x4*>(src + i * 8);
;       const int t0 = half * 64 + i * 8;
;       float f0 = __uint_as_float(w[0] << 16) * rs[t0 + 0] * gd, f1 = __uint_as_float(w[0] & 0xffff0000u) * rs[t0 + 1] * gd;
;       float f2 = __uint_as_float(w[1] << 16) * rs[t0 + 2] * gd, f3 = __uint_as_float(w[1] & 0xffff0000u) * rs[t0 + 3] * gd;
;       float f4 = __uint_as_float(w[2] << 16) * rs[t0 + 4] * gd, f5 = __uint_as_float(w[2] & 0xffff0000u) * rs[t0 + 5] * gd;
;       float f6 = __uint_as_float(w[3] << 16) * rs[t0 + 6] * gd, f7 = __uint_as_float(w[3] & 0xffff0000u) * rs[t0 + 7] * gd;
;       u32x4 o = {cvtpk(f0, f1), cvtpk(f2, f3), cvtpk(f4, f5), cvtpk(f6, f7)};
;       *reinterpret_cast<u32x4*>(Vn + dim * 136 + t0) = o;
;     }
;   }
;   __syncthreads();
	v_lshlrev_b32_e32 v16, 16, v26
	v_and_b32_e32 v21, 0xffff0000, v26
	v_lshlrev_b32_e32 v26, 16, v27
	v_and_b32_e32 v27, 0xffff0000, v27
	v_lshlrev_b32_e32 v37, 16, v28
	v_and_b32_e32 v28, 0xffff0000, v28
	v_lshlrev_b32_e32 v38, 16, v29
	v_and_b32_e32 v29, 0xffff0000, v29
	s_waitcnt lgkmcnt(1)
	v_mul_f32_e32 v16, v22, v16
	v_mul_f32_e32 v21, v23, v21
	v_mul_f32_e32 v22, v24, v26
	v_mul_f32_e32 v23, v25, v27
	s_waitcnt lgkmcnt(0)
	v_mul_f32_e32 v24, v30, v37
	v_mul_f32_e32 v25, v31, v28
	v_mul_f32_e32 v26, v32, v38
	v_mul_f32_e32 v27, v33, v29
	v_mul_f32_e32 v28, v35, v22
	v_mul_f32_e32 v23, v35, v23
	v_mul_f32_e32 v24, v35, v24
	v_mul_f32_e32 v25, v35, v25
	v_mul_f32_e32 v26, v35, v26
	v_mul_f32_e32 v27, v35, v27
	v_mul_f32_e32 v16, v35, v16
	v_mul_f32_e32 v21, v35, v21
	v_cvt_pk_bf16_f32 v22, v16, v21
	v_cvt_pk_bf16_f32 v23, v28, v23
	v_cvt_pk_bf16_f32 v24, v24, v25
	v_cvt_pk_bf16_f32 v25, v26, v27
	global_load_dwordx4 v[26:29], v[18:19], off offset:80
	ds_write_b128 v34, v[22:25] offset:1088
	ds_read_b128 v[22:25], v36 offset:160
	ds_read_b128 v[30:33], v36 offset:176
	s_waitcnt vmcnt(0)
	v_lshlrev_b32_e32 v16, 16, v26
	v_and_b32_e32 v21, 0xffff0000, v26
	v_lshlrev_b32_e32 v26, 16, v27
	v_and_b32_e32 v27, 0xffff0000, v27
	v_lshlrev_b32_e32 v37, 16, v28
	v_and_b32_e32 v28, 0xffff0000, v28
	v_lshlrev_b32_e32 v38, 16, v29
	v_and_b32_e32 v29, 0xffff0000, v29
	s_waitcnt lgkmcnt(1)
	v_mul_f32_e32 v16, v22, v16
	v_mul_f32_e32 v21, v23, v21
	v_mul_f32_e32 v22, v24, v26
	v_mul_f32_e32 v23, v25, v27
	s_waitcnt lgkmcnt(0)
	v_mul_f32_e32 v24, v30, v37
	v_mul_f32_e32 v25, v31, v28
	v_mul_f32_e32 v26, v32, v38
	v_mul_f32_e32 v27, v33, v29
	v_mul_f32_e32 v28, v35, v22
	v_mul_f32_e32 v23, v35, v23
	v_mul_f32_e32 v24, v35, v24
	v_mul_f32_e32 v25, v35, v25
	v_mul_f32_e32 v26, v35, v26
	v_mul_f32_e32 v27, v35, v27
	v_mul_f32_e32 v16, v35, v16
	v_mul_f32_e32 v21, v35, v21
	v_cvt_pk_bf16_f32 v22, v16, v21
	v_cvt_pk_bf16_f32 v23, v28, v23
	v_cvt_pk_bf16_f32 v24, v24, v25
	v_cvt_pk_bf16_f32 v25, v26, v27
	global_load_dwordx4 v[26:29], v[18:19], off offset:96
	ds_write_b128 v34, v[22:25] offset:1104
	ds_read_b128 v[22:25], v36 offset:192
	ds_read_b128 v[30:33], v36 offset:208
	s_waitcnt vmcnt(0)
	v_lshlrev_b32_e32 v16, 16, v26
	v_and_b32_e32 v21, 0xffff0000, v26
	v_lshlrev_b32_e32 v26, 16, v27
	v_and_b32_e32 v27, 0xffff0000, v27
	v_lshlrev_b32_e32 v37, 16, v28
	v_and_b32_e32 v28, 0xffff0000, v28
	v_lshlrev_b32_e32 v38, 16, v29
	v_and_b32_e32 v29, 0xffff0000, v29
	s_waitcnt lgkmcnt(1)
	v_mul_f32_e32 v16, v22, v16
	v_mul_f32_e32 v21, v23, v21
	v_mul_f32_e32 v22, v24, v26
	v_mul_f32_e32 v23, v25, v27
	s_waitcnt lgkmcnt(0)
	v_mul_f32_e32 v24, v30, v37
	v_mul_f32_e32 v25, v31, v28
	v_mul_f32_e32 v26, v32, v38
	v_mul_f32_e32 v27, v33, v29
	v_mul_f32_e32 v28, v35, v22
	v_mul_f32_e32 v23, v35, v23
	v_mul_f32_e32 v24, v35, v24
	v_mul_f32_e32 v25, v35, v25
	v_mul_f32_e32 v26, v35, v26
	v_mul_f32_e32 v27, v35, v27
	v_mul_f32_e32 v16, v35, v16
	v_mul_f32_e32 v21, v35, v21
	v_cvt_pk_bf16_f32 v22, v16, v21
	v_cvt_pk_bf16_f32 v23, v28, v23
	v_cvt_pk_bf16_f32 v24, v24, v25
	v_cvt_pk_bf16_f32 v25, v26, v27
	global_load_dwordx4 v[26:29], v[18:19], off offset:112
	v_and_b32_e32 v30, 31, v20
	v_lshlrev_b32_e32 v16, 8, v30
	v_lshlrev_b64 v[18:19], 15, v[70:71]
	v_lshl_or_b32 v78, v76, 14, v16
	v_lshl_add_u64 v[18:19], s[10:11], 0, v[18:19]
	v_lshlrev_b32_e32 v16, 4, v73
	ds_write_b128 v34, v[22:25] offset:1120
	v_lshl_add_u64 v[80:81], v[18:19], 0, v[16:17]
	ds_read_b128 v[18:21], v36 offset:224
	ds_read_b128 v[22:25], v36 offset:240
	v_lshl_add_u64 v[74:75], v[80:81], 0, v[78:79]
	v_lshl_or_b32 v72, v70, 6, v30
	v_lshlrev_b64 v[70:71], 9, v[70:71]
	s_waitcnt vmcnt(0)
	v_lshlrev_b32_e32 v31, 16, v26
	v_and_b32_e32 v26, 0xffff0000, v26
	v_lshlrev_b32_e32 v32, 16, v27
	v_and_b32_e32 v27, 0xffff0000, v27
	v_lshlrev_b32_e32 v33, 16, v28
	v_and_b32_e32 v28, 0xffff0000, v28
	v_lshlrev_b32_e32 v36, 16, v29
	v_and_b32_e32 v29, 0xffff0000, v29
	s_waitcnt lgkmcnt(1)
	v_mul_f32_e32 v18, v18, v31
	v_mul_f32_e32 v19, v19, v26
	v_mul_f32_e32 v20, v20, v32
	v_mul_f32_e32 v21, v21, v27
	s_waitcnt lgkmcnt(0)
	v_mul_f32_e32 v22, v22, v33
	v_mul_f32_e32 v23, v23, v28
	v_mul_f32_e32 v24, v24, v36
	v_mul_f32_e32 v25, v25, v29
	v_mul_f32_e32 v18, v35, v18
	v_mul_f32_e32 v19, v35, v19
	v_mul_f32_e32 v20, v35, v20
	v_mul_f32_e32 v21, v35, v21
	v_mul_f32_e32 v22, v35, v22
	v_mul_f32_e32 v23, v35, v23
	v_mul_f32_e32 v24, v35, v24
	v_mul_f32_e32 v25, v35, v25
	v_cvt_pk_bf16_f32 v18, v18, v19
	v_cvt_pk_bf16_f32 v19, v20, v21
	v_cvt_pk_bf16_f32 v20, v22, v23
	v_cvt_pk_bf16_f32 v21, v24, v25
	ds_write_b128 v34, v[18:21] offset:1136
	s_waitcnt lgkmcnt(0)
	s_barrier
; __device__ __forceinline__ void gmlp_item(PARAMS_T& p, int l, int b, int pos0, int tokrow0) {
;     ...
;   const int g = wid >> 1, th = wid & 1;
;   const bf16* wsb = (const bf16*)(p.ws + OFF_WSBF) + ((size_t)l * 4 + g) * 128 * 128;
;   f32x16 acc[2][2] = {};
; #pragma unroll
;   for (int ks = 0; ks < 8; ++ks) {
;     bf16x8 af[2], bfr[2];
; #pragma unroll
;     for (int tb = 0; tb < 2; ++tb) af[tb] = *reinterpret_cast<const bf16x8*>(wsb + (size_t)(th * 64 + tb * 32 + r32) * 128 + ks * 16 + hi * 8);
; #pragma unroll
;     for (int db = 0; db < 2; ++db) bfr[db] = *reinterpret_cast<const bf16x8*>(Vn + (g * 64 + db * 32 + r32) * 136 + ks * 16 + hi * 8);
; #pragma unroll
;     for (int tb = 0; tb < 2; ++tb)
; #pragma unroll
;       for (int db = 0; db < 2; ++db) acc[tb][db] = __builtin_amdgcn_mfma_f32_32x32x16_bf16(af[tb], bfr[db], acc[tb][db], 0, 0, 0);
;   }
	v_and_b32_e32 v250, 31, v192
	v_bfe_u32 v251, v192, 5, 1
	v_lshrrev_b32_e32 v252, 7, v192
	v_bfe_u32 v253, v192, 6, 1
	v_lshl_or_b32 v254, v252, 6, v250
	v_lshlrev_b32_e32 v172, 1, v254
	v_mul_u32_u24_e32 v254, 0x110, v254
	v_lshl_add_u32 v254, v251, 4, v254
	v_add_u32_e32 v16, 0x400, v254
	v_lshl_or_b32 v254, v253, 6, v250
	v_lshlrev_b32_e32 v254, 8, v254
	v_lshl_or_b32 v254, v251, 4, v254
	v_lshl_add_u32 v254, v252, 15, v254
	v_mov_b32_e32 v162, v254
	v_mov_b32_e32 v163, 0
	v_lshl_add_u64 v[162:163], s[10:11], 0, v[162:163]
	v_mov_b32_e32 v164, 0x2000
	v_mov_b32_e32 v165, 0
	v_lshl_add_u64 v[164:165], v[162:163], 0, v[164:165]
	global_load_dwordx4 v[82:85], v[162:163], off
	global_load_dwordx4 v[86:89], v[164:165], off
	global_load_dwordx4 v[90:93], v[162:163], off offset:32
	global_load_dwordx4 v[94:97], v[164:165], off offset:32
	global_load_dwordx4 v[98:101], v[162:163], off offset:64
	global_load_dwordx4 v[102:105], v[164:165], off offset:64
	global_load_dwordx4 v[106:109], v[162:163], off offset:96
	global_load_dwordx4 v[110:113], v[164:165], off offset:96
	global_load_dwordx4 v[114:117], v[162:163], off offset:128
	global_load_dwordx4 v[118:121], v[164:165], off offset:128
	global_load_dwordx4 v[122:125], v[162:163], off offset:160
	global_load_dwordx4 v[126:129], v[164:165], off offset:160
	global_load_dwordx4 v[130:133], v[162:163], off offset:192
	global_load_dwordx4 v[134:137], v[164:165], off offset:192
	global_load_dwordx4 v[138:141], v[162:163], off offset:224
	global_load_dwordx4 v[142:145], v[164:165], off offset:224
	v_lshlrev_b32_e32 v171, 6, v253
	v_lshl_add_u32 v171, v251, 2, v171
	v_lshl_add_u32 v170, v252, 7, v171
	v_lshlrev_b32_e32 v170, 2, v170
	v_add_u32_e32 v171, s8, v171
	v_add_u32_e32 v254, 0, v171
	v_lshl_add_u32 v162, v254, 9, v172
	v_add_u32_e32 v254, 8, v171
	v_lshl_add_u32 v163, v254, 9, v172
	v_add_u32_e32 v254, 16, v171
	v_lshl_add_u32 v164, v254, 9, v172
	v_add_u32_e32 v254, 24, v171
	v_lshl_add_u32 v165, v254, 9, v172
	v_add_u32_e32 v254, 32, v171
	v_lshl_add_u32 v166, v254, 9, v172
	v_add_u32_e32 v254, 40, v171
	v_lshl_add_u32 v167, v254, 9, v172
	v_add_u32_e32 v254, 48, v171
	v_lshl_add_u32 v168, v254, 9, v172
	v_add_u32_e32 v254, 56, v171
	v_lshl_add_u32 v169, v254, 9, v172
	v_mov_b32_e32 v18, 0
	v_mov_b32_e32 v19, 0
	v_mov_b32_e32 v20, 0
	v_mov_b32_e32 v21, 0
	v_mov_b32_e32 v22, 0
	v_mov_b32_e32 v23, 0
	v_mov_b32_e32 v24, 0
	v_mov_b32_e32 v25, 0
	v_mov_b32_e32 v26, 0
	v_mov_b32_e32 v27, 0
	v_mov_b32_e32 v28, 0
	v_mov_b32_e32 v29, 0
	v_mov_b32_e32 v30, 0
	v_mov_b32_e32 v31, 0
	v_mov_b32_e32 v32, 0
	v_mov_b32_e32 v33, 0
	v_mov_b32_e32 v34, 0
	v_mov_b32_e32 v35, 0
	v_mov_b32_e32 v36, 0
	v_mov_b32_e32 v37, 0
	v_mov_b32_e32 v38, 0
	v_mov_b32_e32 v39, 0
	v_mov_b32_e32 v40, 0
	v_mov_b32_e32 v41, 0
	v_mov_b32_e32 v42, 0
	v_mov_b32_e32 v43, 0
	v_mov_b32_e32 v44, 0
	v_mov_b32_e32 v45, 0
	v_mov_b32_e32 v46, 0
	v_mov_b32_e32 v47, 0
	v_mov_b32_e32 v48, 0
	v_mov_b32_e32 v49, 0
	v_mov_b32_e32 v50, 0
	v_mov_b32_e32 v51, 0
	v_mov_b32_e32 v52, 0
	v_mov_b32_e32 v53, 0
	v_mov_b32_e32 v54, 0
	v_mov_b32_e32 v55, 0
	v_mov_b32_e32 v56, 0
	v_mov_b32_e32 v57, 0
	v_mov_b32_e32 v58, 0
	v_mov_b32_e32 v59, 0
	v_mov_b32_e32 v60, 0
	v_mov_b32_e32 v61, 0
	v_mov_b32_e32 v62, 0
	v_mov_b32_e32 v63, 0
	v_mov_b32_e32 v64, 0
	v_mov_b32_e32 v65, 0
	v_mov_b32_e32 v66, 0
	v_mov_b32_e32 v67, 0
	v_mov_b32_e32 v68, 0
	v_mov_b32_e32 v69, 0
	v_mov_b32_e32 v70, 0
	v_mov_b32_e32 v71, 0
	v_mov_b32_e32 v72, 0
	v_mov_b32_e32 v73, 0
	v_mov_b32_e32 v74, 0
	v_mov_b32_e32 v75, 0
	v_mov_b32_e32 v76, 0
	v_mov_b32_e32 v77, 0
	v_mov_b32_e32 v78, 0
	v_mov_b32_e32 v79, 0
	v_mov_b32_e32 v80, 0
	v_mov_b32_e32 v81, 0
	ds_read_b128 v[146:149], v16 offset:0
	ds_read_b128 v[150:153], v16 offset:8704
	ds_read_b128 v[154:157], v16 offset:32
	ds_read_b128 v[158:161], v16 offset:8736
	ds_read_b128 v[234:237], v16 offset:64
	ds_read_b128 v[238:241], v16 offset:8768
	ds_read_b128 v[242:245], v16 offset:96
	ds_read_b128 v[246:249], v16 offset:8800
	s_waitcnt vmcnt(15) lgkmcnt(7)
	v_mfma_f32_32x32x16_bf16 v[18:33], v[82:85], v[146:149], v[18:33]
	s_waitcnt vmcnt(15) lgkmcnt(6)
	v_mfma_f32_32x32x16_bf16 v[34:49], v[82:85], v[150:153], v[34:49]
	s_waitcnt vmcnt(14)
	v_mfma_f32_32x32x16_bf16 v[50:65], v[86:89], v[146:149], v[50:65]
	v_mfma_f32_32x32x16_bf16 v[66:81], v[86:89], v[150:153], v[66:81]
	s_waitcnt vmcnt(13) lgkmcnt(5)
	v_mfma_f32_32x32x16_bf16 v[18:33], v[90:93], v[154:157], v[18:33]
	s_waitcnt vmcnt(13) lgkmcnt(4)
	v_mfma_f32_32x32x16_bf16 v[34:49], v[90:93], v[158:161], v[34:49]
	s_waitcnt vmcnt(12)
	v_mfma_f32_32x32x16_bf16 v[50:65], v[94:97], v[154:157], v[50:65]
	v_mfma_f32_32x32x16_bf16 v[66:81], v[94:97], v[158:161], v[66:81]
	s_waitcnt vmcnt(11) lgkmcnt(3)
	v_mfma_f32_32x32x16_bf16 v[18:33], v[98:101], v[234:237], v[18:33]
	s_waitcnt vmcnt(11) lgkmcnt(2)
	v_mfma_f32_32x32x16_bf16 v[34:49], v[98:101], v[238:241], v[34:49]
	s_waitcnt vmcnt(10)
	v_mfma_f32_32x32x16_bf16 v[50:65], v[102:105], v[234:237], v[50:65]
	v_mfma_f32_32x32x16_bf16 v[66:81], v[102:105], v[238:241], v[66:81]
	s_waitcnt vmcnt(9) lgkmcnt(1)
	v_mfma_f32_32x32x16_bf16 v[18:33], v[106:109], v[242:245], v[18:33]
	s_waitcnt vmcnt(9) lgkmcnt(0)
	v_mfma_f32_32x32x16_bf16 v[34:49], v[106:109], v[246:249], v[34:49]
	s_waitcnt vmcnt(8)
	v_mfma_f32_32x32x16_bf16 v[50:65], v[110:113], v[242:245], v[50:65]
	v_mfma_f32_32x32x16_bf16 v[66:81], v[110:113], v[246:249], v[66:81]
	ds_read_b128 v[146:149], v16 offset:128
	ds_read_b128 v[150:153], v16 offset:8832
	ds_read_b128 v[154:157], v16 offset:160
	ds_read_b128 v[158:161], v16 offset:8864
	ds_read_b128 v[234:237], v16 offset:192
	ds_read_b128 v[238:241], v16 offset:8896
	ds_read_b128 v[242:245], v16 offset:224
	ds_read_b128 v[246:249], v16 offset:8928
	s_waitcnt vmcnt(7) lgkmcnt(7)
; __device__ __forceinline__ unsigned short bf1(float a) { return (unsigned short)(cvtpk(a, 0.f) & 0xffffu); }
; __device__ __forceinline__ int crow(int r, int hi) { return (r & 3) + 8 * (r >> 2) + 4 * hi; }
; __device__ __forceinline__ void gmlp_item(PARAMS_T& p, int l, int b, int pos0, int tokrow0) {
;     ...
; #pragma unroll
;   for (int ks = 0; ks < 8; ++ks) {
;     bf16x8 af[2], bfr[2];
; #pragma unroll
;     for (int tb = 0; tb < 2; ++tb) af[tb] = *reinterpret_cast<const bf16x8*>(wsb + (size_t)(th * 64 + tb * 32 + r32) * 128 + ks * 16 + hi * 8);
; #pragma unroll
;     for (int db = 0; db < 2; ++db) bfr[db] = *reinterpret_cast<const bf16x8*>(Vn + (g * 64 + db * 32 + r32) * 136 + ks * 16 + hi * 8);
; #pragma unroll
;     for (int tb = 0; tb < 2; ++tb)
; #pragma unroll
;       for (int db = 0; db < 2; ++db) acc[tb][db] = __builtin_amdgcn_mfma_f32_32x32x16_bf16(af[tb], bfr[db], acc[tb][db], 0, 0, 0);
;   }
;   const float* bs = p.gm_bs + ((size_t)l * 4 + g) * 128;
;   const unsigned short* u = (const unsigned short*)(p.ws + OFF_U);
;   unsigned short* outp = (unsigned short*)(p.ws + OFF_ACTA);
; #pragma unroll
;   for (int tb = 0; tb < 2; ++tb)
; #pragma unroll
;     for (int r = 0; r < 16; ++r) {
;       const int t = th * 64 + tb * 32 + crow(r, hi);
;       const float bt = bs[t];
; #pragma unroll
;       for (int db = 0; db < 2; ++db) {
;         const int d = g * 64 + db * 32 + r32;
;         const float uv = __uint_as_float(((unsigned)u[(size_t)(tokrow0 + t) * 256 + d]) << 16);
;         outp[(size_t)(tokrow0 + t) * 1024 + 256 + d] = bf1(uv * (acc[tb][db][r] + bt));
;       }
;     }
	v_mfma_f32_32x32x16_bf16 v[18:33], v[114:117], v[146:149], v[18:33]
	s_waitcnt vmcnt(7) lgkmcnt(6)
	v_mfma_f32_32x32x16_bf16 v[34:49], v[114:117], v[150:153], v[34:49]
	s_waitcnt vmcnt(6)
	v_mfma_f32_32x32x16_bf16 v[50:65], v[118:121], v[146:149], v[50:65]
	v_mfma_f32_32x32x16_bf16 v[66:81], v[118:121], v[150:153], v[66:81]
	s_waitcnt vmcnt(5) lgkmcnt(5)
	v_mfma_f32_32x32x16_bf16 v[18:33], v[122:125], v[154:157], v[18:33]
	s_waitcnt vmcnt(5) lgkmcnt(4)
	v_mfma_f32_32x32x16_bf16 v[34:49], v[122:125], v[158:161], v[34:49]
	s_waitcnt vmcnt(4)
	v_mfma_f32_32x32x16_bf16 v[50:65], v[126:129], v[154:157], v[50:65]
	v_mfma_f32_32x32x16_bf16 v[66:81], v[126:129], v[158:161], v[66:81]
	s_waitcnt vmcnt(3) lgkmcnt(3)
	v_mfma_f32_32x32x16_bf16 v[18:33], v[130:133], v[234:237], v[18:33]
	s_waitcnt vmcnt(3) lgkmcnt(2)
	v_mfma_f32_32x32x16_bf16 v[34:49], v[130:133], v[238:241], v[34:49]
	s_waitcnt vmcnt(2)
	v_mfma_f32_32x32x16_bf16 v[50:65], v[134:137], v[234:237], v[50:65]
	v_mfma_f32_32x32x16_bf16 v[66:81], v[134:137], v[238:241], v[66:81]
	s_waitcnt vmcnt(1) lgkmcnt(1)
	v_mfma_f32_32x32x16_bf16 v[18:33], v[138:141], v[242:245], v[18:33]
	s_waitcnt vmcnt(1) lgkmcnt(0)
	v_mfma_f32_32x32x16_bf16 v[34:49], v[138:141], v[246:249], v[34:49]
	s_waitcnt vmcnt(0)
	v_mfma_f32_32x32x16_bf16 v[50:65], v[142:145], v[242:245], v[50:65]
	v_mfma_f32_32x32x16_bf16 v[66:81], v[142:145], v[246:249], v[66:81]
	v_bfe_u32 v250, v192, 3, 3
	v_and_b32_e32 v251, 7, v192
	v_bfe_u32 v253, v192, 6, 1
	v_lshrrev_b32_e32 v254, 7, v192
	v_lshl_add_u32 v167, v253, 6, v250
	v_lshl_add_u32 v166, v254, 7, v167
	v_lshlrev_b32_e32 v166, 2, v166
	v_add_u32_e32 v167, s8, v167
	v_lshlrev_b32_e32 v168, 7, v254
	v_lshl_add_u32 v168, v251, 4, v168
	v_lshl_add_u32 v164, v167, 9, v168
	v_lshl_add_u32 v165, v167, 11, v168
	v_add_u32_e32 v167, 0x0, v164
	global_load_dwordx4 v[82:85], v167, s[80:81]
	v_add_u32_e32 v168, 0x1000, v164
	global_load_dwordx4 v[86:89], v168, s[80:81]
	v_add_u32_e32 v167, 0x2000, v164
	global_load_dwordx4 v[90:93], v167, s[80:81]
	v_add_u32_e32 v168, 0x3000, v164
	global_load_dwordx4 v[94:97], v168, s[80:81]
	v_add_u32_e32 v167, 0x4000, v164
	global_load_dwordx4 v[98:101], v167, s[80:81]
	v_add_u32_e32 v168, 0x5000, v164
	global_load_dwordx4 v[102:105], v168, s[80:81]
	v_add_u32_e32 v167, 0x6000, v164
	global_load_dwordx4 v[106:109], v167, s[80:81]
	v_add_u32_e32 v168, 0x7000, v164
	global_load_dwordx4 v[110:113], v168, s[80:81]
	global_load_dword v114, v166, s[4:5]
	global_load_dword v115, v166, s[4:5] offset:32
	global_load_dword v116, v166, s[4:5] offset:64
	global_load_dword v117, v166, s[4:5] offset:96
	global_load_dword v118, v166, s[4:5] offset:128
	global_load_dword v119, v166, s[4:5] offset:160
	global_load_dword v120, v166, s[4:5] offset:192
	global_load_dword v121, v166, s[4:5] offset:224
	v_lshrrev_b32_e32 v253, 6, v192
	v_mul_u32_u24_e32 v253, 0x1100, v253
	v_add_u32_e32 v253, 0x11800, v253
	v_mul_u32_u24_e32 v163, 0x110, v250
	v_lshl_add_u32 v163, v251, 5, v163
	v_add_u32_e32 v163, v253, v163
	v_and_b32_e32 v250, 31, v192
	v_bfe_u32 v251, v192, 5, 1
	v_mul_u32_u24_e32 v162, 0x440, v251
	v_lshl_add_u32 v162, v250, 2, v162
	v_add_u32_e32 v162, v253, v162
	ds_write_b32 v162, v18
	ds_write_b32 v162, v34 offset:128
	ds_write_b32 v162, v19 offset:272
	ds_write_b32 v162, v35 offset:400
	ds_write_b32 v162, v20 offset:544
	ds_write_b32 v162, v36 offset:672
	ds_write_b32 v162, v21 offset:816
	ds_write_b32 v162, v37 offset:944
	ds_write_b32 v162, v22 offset:2176
	ds_write_b32 v162, v38 offset:2304
	ds_write_b32 v162, v23 offset:2448
	ds_write_b32 v162, v39 offset:2576
	ds_write_b32 v162, v24 offset:2720
	ds_write_b32 v162, v40 offset:2848
	ds_write_b32 v162, v25 offset:2992
	ds_write_b32 v162, v41 offset:3120
	ds_read_b128 v[122:125], v163 offset:0
	ds_read_b128 v[126:129], v163 offset:16
	ds_read_b128 v[130:133], v163 offset:2176
	ds_read_b128 v[134:137], v163 offset:2192
	s_waitcnt vmcnt(0)
	s_waitcnt lgkmcnt(2)
	v_add_f32_e32 v252, v122, v114
	v_lshlrev_b32_e32 v253, 16, v82
	v_mul_f32_e32 v250, v252, v253
	v_add_f32_e32 v252, v123, v114
	v_and_b32_e32 v253, 0xffff0000, v82
	v_mul_f32_e32 v251, v252, v253
	v_cvt_pk_bf16_f32 v154, v250, v251
	v_add_f32_e32 v252, v124, v114
	v_lshlrev_b32_e32 v253, 16, v83
	v_mul_f32_e32 v250, v252, v253
	v_add_f32_e32 v252, v125, v114
	v_and_b32_e32 v253, 0xffff0000, v83
	v_mul_f32_e32 v251, v252, v253
	v_cvt_pk_bf16_f32 v155, v250, v251
	v_add_f32_e32 v252, v126, v114
	v_lshlrev_b32_e32 v253, 16, v84
	v_mul_f32_e32 v250, v252, v253
	v_add_f32_e32 v252, v127, v114
	v_and_b32_e32 v253, 0xffff0000, v84
	v_mul_f32_e32 v251, v252, v253
	v_cvt_pk_bf16_f32 v156, v250, v251
	v_add_f32_e32 v252, v128, v114
	v_lshlrev_b32_e32 v253, 16, v85
	v_mul_f32_e32 v250, v252, v253
	v_add_f32_e32 v252, v129, v114
	v_and_b32_e32 v253, 0xffff0000, v85
	v_mul_f32_e32 v251, v252, v253
	v_cvt_pk_bf16_f32 v157, v250, v251
	v_add_u32_e32 v167, 0x0, v165
	global_store_dwordx4 v167, v[154:157], s[0:1]
	s_waitcnt lgkmcnt(0)
; __device__ __forceinline__ unsigned short bf1(float a) { return (unsigned short)(cvtpk(a, 0.f) & 0xffffu); }
; __device__ __forceinline__ int crow(int r, int hi) { return (r & 3) + 8 * (r >> 2) + 4 * hi; }
; __device__ __forceinline__ void gmlp_item(PARAMS_T& p, int l, int b, int pos0, int tokrow0) {
;     ...
; #pragma unroll
;   for (int tb = 0; tb < 2; ++tb)
; #pragma unroll
;     for (int r = 0; r < 16; ++r) {
;       const int t = th * 64 + tb * 32 + crow(r, hi);
;       const float bt = bs[t];
; #pragma unroll
;       for (int db = 0; db < 2; ++db) {
;         const int d = g * 64 + db * 32 + r32;
;         const float uv = __uint_as_float(((unsigned)u[(size_t)(tokrow0 + t) * 256 + d]) << 16);
;         outp[(size_t)(tokrow0 + t) * 1024 + 256 + d] = bf1(uv * (acc[tb][db][r] + bt));
;       }
;     }
	v_add_f32_e32 v252, v130, v115
	v_lshlrev_b32_e32 v253, 16, v86
	v_mul_f32_e32 v250, v252, v253
	v_add_f32_e32 v252, v131, v115
	v_and_b32_e32 v253, 0xffff0000, v86
	v_mul_f32_e32 v251, v252, v253
	v_cvt_pk_bf16_f32 v158, v250, v251
	v_add_f32_e32 v252, v132, v115
	v_lshlrev_b32_e32 v253, 16, v87
	v_mul_f32_e32 v250, v252, v253
	v_add_f32_e32 v252, v133, v115
	v_and_b32_e32 v253, 0xffff0000, v87
	v_mul_f32_e32 v251, v252, v253
	v_cvt_pk_bf16_f32 v159, v250, v251
	v_add_f32_e32 v252, v134, v115
	v_lshlrev_b32_e32 v253, 16, v88
	v_mul_f32_e32 v250, v252, v253
	v_add_f32_e32 v252, v135, v115
	v_and_b32_e32 v253, 0xffff0000, v88
	v_mul_f32_e32 v251, v252, v253
	v_cvt_pk_bf16_f32 v160, v250, v251
	v_add_f32_e32 v252, v136, v115
	v_lshlrev_b32_e32 v253, 16, v89
	v_mul_f32_e32 v250, v252, v253
	v_add_f32_e32 v252, v137, v115
	v_and_b32_e32 v253, 0xffff0000, v89
	v_mul_f32_e32 v251, v252, v253
	v_cvt_pk_bf16_f32 v161, v250, v251
	v_add_u32_e32 v168, 0x4000, v165
	global_store_dwordx4 v168, v[158:161], s[0:1]
	ds_write_b32 v162, v26
	ds_write_b32 v162, v42 offset:128
	ds_write_b32 v162, v27 offset:272
	ds_write_b32 v162, v43 offset:400
	ds_write_b32 v162, v28 offset:544
	ds_write_b32 v162, v44 offset:672
	ds_write_b32 v162, v29 offset:816
	ds_write_b32 v162, v45 offset:944
	ds_write_b32 v162, v30 offset:2176
	ds_write_b32 v162, v46 offset:2304
	ds_write_b32 v162, v31 offset:2448
	ds_write_b32 v162, v47 offset:2576
	ds_write_b32 v162, v32 offset:2720
	ds_write_b32 v162, v48 offset:2848
	ds_write_b32 v162, v33 offset:2992
	ds_write_b32 v162, v49 offset:3120
	ds_read_b128 v[122:125], v163 offset:0
	ds_read_b128 v[126:129], v163 offset:16
	ds_read_b128 v[130:133], v163 offset:2176
	ds_read_b128 v[134:137], v163 offset:2192
	s_waitcnt lgkmcnt(2)
	v_add_f32_e32 v252, v122, v116
	v_lshlrev_b32_e32 v253, 16, v90
	v_mul_f32_e32 v250, v252, v253
	v_add_f32_e32 v252, v123, v116
	v_and_b32_e32 v253, 0xffff0000, v90
	v_mul_f32_e32 v251, v252, v253
	v_cvt_pk_bf16_f32 v154, v250, v251
	v_add_f32_e32 v252, v124, v116
	v_lshlrev_b32_e32 v253, 16, v91
	v_mul_f32_e32 v250, v252, v253
	v_add_f32_e32 v252, v125, v116
	v_and_b32_e32 v253, 0xffff0000, v91
	v_mul_f32_e32 v251, v252, v253
	v_cvt_pk_bf16_f32 v155, v250, v251
	v_add_f32_e32 v252, v126, v116
	v_lshlrev_b32_e32 v253, 16, v92
	v_mul_f32_e32 v250, v252, v253
	v_add_f32_e32 v252, v127, v116
	v_and_b32_e32 v253, 0xffff0000, v92
	v_mul_f32_e32 v251, v252, v253
	v_cvt_pk_bf16_f32 v156, v250, v251
	v_add_f32_e32 v252, v128, v116
	v_lshlrev_b32_e32 v253, 16, v93
	v_mul_f32_e32 v250, v252, v253
	v_add_f32_e32 v252, v129, v116
	v_and_b32_e32 v253, 0xffff0000, v93
	v_mul_f32_e32 v251, v252, v253
	v_cvt_pk_bf16_f32 v157, v250, v251
	v_add_u32_e32 v167, 0x8000, v165
	global_store_dwordx4 v167, v[154:157], s[0:1]
	s_waitcnt lgkmcnt(0)
	v_add_f32_e32 v252, v130, v117
	v_lshlrev_b32_e32 v253, 16, v94
	v_mul_f32_e32 v250, v252, v253
	v_add_f32_e32 v252, v131, v117
	v_and_b32_e32 v253, 0xffff0000, v94
	v_mul_f32_e32 v251, v252, v253
	v_cvt_pk_bf16_f32 v158, v250, v251
	v_add_f32_e32 v252, v132, v117
	v_lshlrev_b32_e32 v253, 16, v95
	v_mul_f32_e32 v250, v252, v253
	v_add_f32_e32 v252, v133, v117
	v_and_b32_e32 v253, 0xffff0000, v95
	v_mul_f32_e32 v251, v252, v253
	v_cvt_pk_bf16_f32 v159, v250, v251
	v_add_f32_e32 v252, v134, v117
	v_lshlrev_b32_e32 v253, 16, v96
	v_mul_f32_e32 v250, v252, v253
	v_add_f32_e32 v252, v135, v117
	v_and_b32_e32 v253, 0xffff0000, v96
	v_mul_f32_e32 v251, v252, v253
	v_cvt_pk_bf16_f32 v160, v250, v251
	v_add_f32_e32 v252, v136, v117
	v_lshlrev_b32_e32 v253, 16, v97
	v_mul_f32_e32 v250, v252, v253
	v_add_f32_e32 v252, v137, v117
	v_and_b32_e32 v253, 0xffff0000, v97
	v_mul_f32_e32 v251, v252, v253
	v_cvt_pk_bf16_f32 v161, v250, v251
	v_add_u32_e32 v168, 0xc000, v165
	global_store_dwordx4 v168, v[158:161], s[0:1]
	ds_write_b32 v162, v50
	ds_write_b32 v162, v66 offset:128
	ds_write_b32 v162, v51 offset:272
	ds_write_b32 v162, v67 offset:400
	ds_write_b32 v162, v52 offset:544
	ds_write_b32 v162, v68 offset:672
	ds_write_b32 v162, v53 offset:816
	ds_write_b32 v162, v69 offset:944
	ds_write_b32 v162, v54 offset:2176
	ds_write_b32 v162, v70 offset:2304
	ds_write_b32 v162, v55 offset:2448
	ds_write_b32 v162, v71 offset:2576
	ds_write_b32 v162, v56 offset:2720
	ds_write_b32 v162, v72 offset:2848
	ds_write_b32 v162, v57 offset:2992
	ds_write_b32 v162, v73 offset:3120
	ds_read_b128 v[122:125], v163 offset:0
	ds_read_b128 v[126:129], v163 offset:16
	ds_read_b128 v[130:133], v163 offset:2176
	ds_read_b128 v[134:137], v163 offset:2192
	s_waitcnt lgkmcnt(2)
; __device__ __forceinline__ unsigned short bf1(float a) { return (unsigned short)(cvtpk(a, 0.f) & 0xffffu); }
; __device__ __forceinline__ int crow(int r, int hi) { return (r & 3) + 8 * (r >> 2) + 4 * hi; }
; __device__ __forceinline__ void gmlp_item(PARAMS_T& p, int l, int b, int pos0, int tokrow0) {
;     ...
; #pragma unroll
;   for (int tb = 0; tb < 2; ++tb)
; #pragma unroll
;     for (int r = 0; r < 16; ++r) {
;       const int t = th * 64 + tb * 32 + crow(r, hi);
;       const float bt = bs[t];
; #pragma unroll
;       for (int db = 0; db < 2; ++db) {
;         const int d = g * 64 + db * 32 + r32;
;         const float uv = __uint_as_float(((unsigned)u[(size_t)(tokrow0 + t) * 256 + d]) << 16);
;         outp[(size_t)(tokrow0 + t) * 1024 + 256 + d] = bf1(uv * (acc[tb][db][r] + bt));
;       }
;     }
	v_add_f32_e32 v252, v122, v118
	v_lshlrev_b32_e32 v253, 16, v98
	v_mul_f32_e32 v250, v252, v253
	v_add_f32_e32 v252, v123, v118
	v_and_b32_e32 v253, 0xffff0000, v98
	v_mul_f32_e32 v251, v252, v253
	v_cvt_pk_bf16_f32 v154, v250, v251
	v_add_f32_e32 v252, v124, v118
	v_lshlrev_b32_e32 v253, 16, v99
	v_mul_f32_e32 v250, v252, v253
	v_add_f32_e32 v252, v125, v118
	v_and_b32_e32 v253, 0xffff0000, v99
	v_mul_f32_e32 v251, v252, v253
	v_cvt_pk_bf16_f32 v155, v250, v251
	v_add_f32_e32 v252, v126, v118
	v_lshlrev_b32_e32 v253, 16, v100
	v_mul_f32_e32 v250, v252, v253
	v_add_f32_e32 v252, v127, v118
	v_and_b32_e32 v253, 0xffff0000, v100
	v_mul_f32_e32 v251, v252, v253
	v_cvt_pk_bf16_f32 v156, v250, v251
	v_add_f32_e32 v252, v128, v118
	v_lshlrev_b32_e32 v253, 16, v101
	v_mul_f32_e32 v250, v252, v253
	v_add_f32_e32 v252, v129, v118
	v_and_b32_e32 v253, 0xffff0000, v101
	v_mul_f32_e32 v251, v252, v253
	v_cvt_pk_bf16_f32 v157, v250, v251
	v_add_u32_e32 v167, 0x10000, v165
	global_store_dwordx4 v167, v[154:157], s[0:1]
	s_waitcnt lgkmcnt(0)
	v_add_f32_e32 v252, v130, v119
	v_lshlrev_b32_e32 v253, 16, v102
	v_mul_f32_e32 v250, v252, v253
	v_add_f32_e32 v252, v131, v119
	v_and_b32_e32 v253, 0xffff0000, v102
	v_mul_f32_e32 v251, v252, v253
	v_cvt_pk_bf16_f32 v158, v250, v251
	v_add_f32_e32 v252, v132, v119
	v_lshlrev_b32_e32 v253, 16, v103
	v_mul_f32_e32 v250, v252, v253
	v_add_f32_e32 v252, v133, v119
	v_and_b32_e32 v253, 0xffff0000, v103
	v_mul_f32_e32 v251, v252, v253
	v_cvt_pk_bf16_f32 v159, v250, v251
	v_add_f32_e32 v252, v134, v119
	v_lshlrev_b32_e32 v253, 16, v104
	v_mul_f32_e32 v250, v252, v253
	v_add_f32_e32 v252, v135, v119
	v_and_b32_e32 v253, 0xffff0000, v104
	v_mul_f32_e32 v251, v252, v253
	v_cvt_pk_bf16_f32 v160, v250, v251
	v_add_f32_e32 v252, v136, v119
	v_lshlrev_b32_e32 v253, 16, v105
	v_mul_f32_e32 v250, v252, v253
	v_add_f32_e32 v252, v137, v119
	v_and_b32_e32 v253, 0xffff0000, v105
	v_mul_f32_e32 v251, v252, v253
	v_cvt_pk_bf16_f32 v161, v250, v251
	v_add_u32_e32 v168, 0x14000, v165
	global_store_dwordx4 v168, v[158:161], s[0:1]
	ds_write_b32 v162, v58
	ds_write_b32 v162, v74 offset:128
	ds_write_b32 v162, v59 offset:272
	ds_write_b32 v162, v75 offset:400
	ds_write_b32 v162, v60 offset:544
	ds_write_b32 v162, v76 offset:672
	ds_write_b32 v162, v61 offset:816
	ds_write_b32 v162, v77 offset:944
	ds_write_b32 v162, v62 offset:2176
	ds_write_b32 v162, v78 offset:2304
	ds_write_b32 v162, v63 offset:2448
	ds_write_b32 v162, v79 offset:2576
	ds_write_b32 v162, v64 offset:2720
	ds_write_b32 v162, v80 offset:2848
	ds_write_b32 v162, v65 offset:2992
	ds_write_b32 v162, v81 offset:3120
	ds_read_b128 v[122:125], v163 offset:0
	ds_read_b128 v[126:129], v163 offset:16
	ds_read_b128 v[130:133], v163 offset:2176
	ds_read_b128 v[134:137], v163 offset:2192
	s_waitcnt lgkmcnt(2)
	v_add_f32_e32 v252, v122, v120
	v_lshlrev_b32_e32 v253, 16, v106
	v_mul_f32_e32 v250, v252, v253
	v_add_f32_e32 v252, v123, v120
	v_and_b32_e32 v253, 0xffff0000, v106
	v_mul_f32_e32 v251, v252, v253
	v_cvt_pk_bf16_f32 v154, v250, v251
	v_add_f32_e32 v252, v124, v120
	v_lshlrev_b32_e32 v253, 16, v107
	v_mul_f32_e32 v250, v252, v253
	v_add_f32_e32 v252, v125, v120
	v_and_b32_e32 v253, 0xffff0000, v107
	v_mul_f32_e32 v251, v252, v253
	v_cvt_pk_bf16_f32 v155, v250, v251
	v_add_f32_e32 v252, v126, v120
	v_lshlrev_b32_e32 v253, 16, v108
	v_mul_f32_e32 v250, v252, v253
	v_add_f32_e32 v252, v127, v120
	v_and_b32_e32 v253, 0xffff0000, v108
	v_mul_f32_e32 v251, v252, v253
	v_cvt_pk_bf16_f32 v156, v250, v251
	v_add_f32_e32 v252, v128, v120
	v_lshlrev_b32_e32 v253, 16, v109
	v_mul_f32_e32 v250, v252, v253
	v_add_f32_e32 v252, v129, v120
	v_and_b32_e32 v253, 0xffff0000, v109
	v_mul_f32_e32 v251, v252, v253
	v_cvt_pk_bf16_f32 v157, v250, v251
	v_add_u32_e32 v167, 0x18000, v165
	global_store_dwordx4 v167, v[154:157], s[0:1]
	s_waitcnt lgkmcnt(0)
	v_add_f32_e32 v252, v130, v121
	v_lshlrev_b32_e32 v253, 16, v110
	v_mul_f32_e32 v250, v252, v253
	v_add_f32_e32 v252, v131, v121
	v_and_b32_e32 v253, 0xffff0000, v110
	v_mul_f32_e32 v251, v252, v253
	v_cvt_pk_bf16_f32 v158, v250, v251
	v_add_f32_e32 v252, v132, v121
	v_lshlrev_b32_e32 v253, 16, v111
	v_mul_f32_e32 v250, v252, v253
	v_add_f32_e32 v252, v133, v121
	v_and_b32_e32 v253, 0xffff0000, v111
	v_mul_f32_e32 v251, v252, v253
	v_cvt_pk_bf16_f32 v159, v250, v251
	v_add_f32_e32 v252, v134, v121
	v_lshlrev_b32_e32 v253, 16, v112
	v_mul_f32_e32 v250, v252, v253
	v_add_f32_e32 v252, v135, v121
	v_and_b32_e32 v253, 0xffff0000, v112
	v_mul_f32_e32 v251, v252, v253
	v_cvt_pk_bf16_f32 v160, v250, v251
	v_add_f32_e32 v252, v136, v121
	v_lshlrev_b32_e32 v253, 16, v113
	v_mul_f32_e32 v250, v252, v253
	v_add_f32_e32 v252, v137, v121
	v_and_b32_e32 v253, 0xffff0000, v113
	v_mul_f32_e32 v251, v252, v253
	v_cvt_pk_bf16_f32 v161, v250, v251
	v_add_u32_e32 v168, 0x1c000, v165
	global_store_dwordx4 v168, v[158:161], s[0:1]
	s_mov_b64 s[4:5], 0

; __device__ __forceinline__ void gmlp_item(PARAMS_T& p, int l, int b, int pos0, int tokrow0) {
;     ...
;   {
;     const int dim = tid >> 1, half = tid & 1;
;     const float gd = p.gm_v_g[l * 256 + dim];
;     const unsigned short* src = (const unsigned short*)(p.ws + OFF_VT) + ((size_t)b * 256 + dim) * PTOK + pos0 + half * 64;
; #pragma unroll
;     for (int i = 0; i < 8; ++i) {
;       u32x4 w = *reinterpret_cast<const u32x4*>(src + i * 8);
;       const int t0 = half * 64 + i * 8;
;       float f0 = __uint_as_float(w[0] << 16) * rs[t0 + 0] * gd, f1 = __uint_as_float(w[0] & 0xffff0000u) * rs[t0 + 1] * gd;
;       float f2 = __uint_as_float(w[1] << 16) * rs[t0 + 2] * gd, f3 = __uint_as_float(w[1] & 0xffff0000u) * rs[t0 + 3] * gd;
;       float f4 = __uint_as_float(w[2] << 16) * rs[t0 + 4] * gd, f5 = __uint_as_float(w[2] & 0xffff0000u) * rs[t0 + 5] * gd;
;       float f6 = __uint_as_float(w[3] << 16) * rs[t0 + 6] * gd, f7 = __uint_as_float(w[3] & 0xffff0000u) * rs[t0 + 7] * gd;
;       u32x4 o = {cvtpk(f0, f1), cvtpk(f2, f3), cvtpk(f4, f5), cvtpk(f6, f7)};
;       *reinterpret_cast<u32x4*>(Vn + dim * 136 + t0) = o;
;     }
;   }
.LBB0_1887:
	s_or_b64 exec, exec, s[6:7]
	v_ashrrev_i32_e32 v34, 1, v20
	v_ashrrev_i32_e32 v35, 31, v34
	s_lshl_b64 s[6:7], s[80:81], 8
	v_lshl_add_u64 v[18:19], s[6:7], 0, v[34:35]
	v_readlane_b32 s6, v255, 24
	v_readlane_b32 s7, v255, 25
	s_movk_i32 s5, 0x4200
	v_lshlrev_b32_e32 v16, 6, v20
	v_mov_b64_e32 v[22:23], s[6:7]
	v_mad_u64_u32 v[22:23], s[6:7], v18, s5, v[22:23]
	v_mad_i32_i24 v23, v19, s5, v23
	s_lshl_b32 s80, s4, 1
	v_and_b32_e32 v21, 64, v16
	v_lshl_add_u64 v[18:19], v[22:23], 0, s[80:81]
	v_lshlrev_b32_e32 v16, 1, v21
	v_lshl_add_u64 v[18:19], v[18:19], 0, v[16:17]
	s_waitcnt lgkmcnt(0)
	s_barrier
	global_load_dwordx4 v[22:25], v[18:19], off
	s_load_dwordx2 s[4:5], s[0:1], 0x58
	s_load_dwordx2 s[6:7], s[0:1], 0x68
	v_lshl_add_u32 v36, v21, 2, 0
	v_readlane_b32 s8, v255, 38
	v_bfe_u32 v73, v20, 5, 1
	s_waitcnt lgkmcnt(0)
	v_lshl_add_u64 v[26:27], v[34:35], 2, s[4:5]
	global_load_dword v35, v[26:27], off offset:1024
	ds_read_b128 v[26:29], v36
	ds_read_b128 v[30:33], v36 offset:16
	s_movk_i32 s4, 0x110
	v_bfe_u32 v76, v20, 6, 1
	v_readlane_b32 s9, v255, 39
	v_mov_b32_e32 v79, v17
	s_waitcnt vmcnt(1)
	v_lshlrev_b32_e32 v21, 16, v22
	v_and_b32_e32 v22, 0xffff0000, v22
	v_lshlrev_b32_e32 v37, 16, v23
	v_and_b32_e32 v23, 0xffff0000, v23
	v_lshlrev_b32_e32 v38, 16, v24
	v_and_b32_e32 v24, 0xffff0000, v24
	v_lshlrev_b32_e32 v39, 16, v25
	v_and_b32_e32 v25, 0xffff0000, v25
	s_waitcnt lgkmcnt(1)
	v_mul_f32_e32 v21, v26, v21
	v_mul_f32_e32 v22, v27, v22
	v_mul_f32_e32 v26, v28, v37
	v_mul_f32_e32 v23, v29, v23
	s_waitcnt lgkmcnt(0)
	v_mul_f32_e32 v27, v30, v38
	v_mul_f32_e32 v24, v31, v24
	v_mul_f32_e32 v28, v32, v39
	v_mul_f32_e32 v25, v33, v25
	s_waitcnt vmcnt(0)
	v_mul_f32_e32 v22, v35, v22
	v_mul_f32_e32 v26, v35, v26
	v_mul_f32_e32 v23, v35, v23
	v_mul_f32_e32 v27, v35, v27
	v_mul_f32_e32 v24, v35, v24
	v_mul_f32_e32 v28, v35, v28
	v_mul_f32_e32 v25, v35, v25
	v_mul_f32_e32 v21, v35, v21
	v_cvt_pk_bf16_f32 v22, v21, v22
	v_cvt_pk_bf16_f32 v23, v26, v23
	v_cvt_pk_bf16_f32 v24, v27, v24
	v_cvt_pk_bf16_f32 v25, v28, v25
	global_load_dwordx4 v[26:29], v[18:19], off offset:16
	v_mul_lo_u32 v21, v34, s4
	v_add3_u32 v34, 0, v21, v16
	ds_write_b128 v34, v[22:25] offset:1024
	ds_read_b128 v[22:25], v36 offset:32
	ds_read_b128 v[30:33], v36 offset:48
	s_waitcnt vmcnt(0)
	v_lshlrev_b32_e32 v16, 16, v26
	v_and_b32_e32 v21, 0xffff0000, v26
	v_lshlrev_b32_e32 v26, 16, v27
	v_and_b32_e32 v27, 0xffff0000, v27
	v_lshlrev_b32_e32 v37, 16, v28
	v_and_b32_e32 v28, 0xffff0000, v28
	v_lshlrev_b32_e32 v38, 16, v29
	v_and_b32_e32 v29, 0xffff0000, v29
	s_waitcnt lgkmcnt(1)
	v_mul_f32_e32 v16, v22, v16
	v_mul_f32_e32 v21, v23, v21
	v_mul_f32_e32 v22, v24, v26
	v_mul_f32_e32 v23, v25, v27
	s_waitcnt lgkmcnt(0)
	v_mul_f32_e32 v24, v30, v37
	v_mul_f32_e32 v25, v31, v28
	v_mul_f32_e32 v26, v32, v38
	v_mul_f32_e32 v27, v33, v29
	v_mul_f32_e32 v28, v35, v22
	v_mul_f32_e32 v23, v35, v23
	v_mul_f32_e32 v24, v35, v24
	v_mul_f32_e32 v25, v35, v25
	v_mul_f32_e32 v26, v35, v26
	v_mul_f32_e32 v27, v35, v27
	v_mul_f32_e32 v16, v35, v16
	v_mul_f32_e32 v21, v35, v21
	v_cvt_pk_bf16_f32 v22, v16, v21
	v_cvt_pk_bf16_f32 v23, v28, v23
	v_cvt_pk_bf16_f32 v24, v24, v25
	v_cvt_pk_bf16_f32 v25, v26, v27
	global_load_dwordx4 v[26:29], v[18:19], off offset:32
	ds_write_b128 v34, v[22:25] offset:1040
	ds_read_b128 v[22:25], v36 offset:64
	ds_read_b128 v[30:33], v36 offset:80
	s_waitcnt vmcnt(0)
	v_lshlrev_b32_e32 v16, 16, v26
	v_and_b32_e32 v21, 0xffff0000, v26
	v_lshlrev_b32_e32 v26, 16, v27
	v_and_b32_e32 v27, 0xffff0000, v27
	v_lshlrev_b32_e32 v37, 16, v28
	v_and_b32_e32 v28, 0xffff0000, v28
	v_lshlrev_b32_e32 v38, 16, v29
	v_and_b32_e32 v29, 0xffff0000, v29
	s_waitcnt lgkmcnt(1)
	v_mul_f32_e32 v16, v22, v16
	v_mul_f32_e32 v21, v23, v21
	v_mul_f32_e32 v22, v24, v26
	v_mul_f32_e32 v23, v25, v27
	s_waitcnt lgkmcnt(0)
	v_mul_f32_e32 v24, v30, v37
	v_mul_f32_e32 v25, v31, v28
	v_mul_f32_e32 v26, v32, v38
	v_mul_f32_e32 v27, v33, v29
	v_mul_f32_e32 v28, v35, v22
	v_mul_f32_e32 v23, v35, v23
	v_mul_f32_e32 v24, v35, v24
	v_mul_f32_e32 v25, v35, v25
	v_mul_f32_e32 v26, v35, v26
	v_mul_f32_e32 v27, v35, v27
	v_mul_f32_e32 v16, v35, v16
	v_mul_f32_e32 v21, v35, v21
	v_cvt_pk_bf16_f32 v22, v16, v21
	v_cvt_pk_bf16_f32 v23, v28, v23
	v_cvt_pk_bf16_f32 v24, v24, v25
	v_cvt_pk_bf16_f32 v25, v26, v27
	global_load_dwordx4 v[26:29], v[18:19], off offset:48
	ds_write_b128 v34, v[22:25] offset:1056
	ds_read_b128 v[22:25], v36 offset:96
	ds_read_b128 v[30:33], v36 offset:112
	s_waitcnt vmcnt(0)
	v_lshlrev_b32_e32 v16, 16, v26
	v_and_b32_e32 v21, 0xffff0000, v26
	v_lshlrev_b32_e32 v26, 16, v27
	v_and_b32_e32 v27, 0xffff0000, v27
	v_lshlrev_b32_e32 v37, 16, v28
	v_and_b32_e32 v28, 0xffff0000, v28
	v_lshlrev_b32_e32 v38, 16, v29
	v_and_b32_e32 v29, 0xffff0000, v29
	s_waitcnt lgkmcnt(1)
	v_mul_f32_e32 v16, v22, v16
	v_mul_f32_e32 v21, v23, v21
	v_mul_f32_e32 v22, v24, v26
	v_mul_f32_e32 v23, v25, v27
	s_waitcnt lgkmcnt(0)
	v_mul_f32_e32 v24, v30, v37
	v_mul_f32_e32 v25, v31, v28
	v_mul_f32_e32 v26, v32, v38
	v_mul_f32_e32 v27, v33, v29
	v_mul_f32_e32 v28, v35, v22
	v_mul_f32_e32 v23, v35, v23
	v_mul_f32_e32 v24, v35, v24
	v_mul_f32_e32 v25, v35, v25
	v_mul_f32_e32 v26, v35, v26
	v_mul_f32_e32 v27, v35, v27
	v_mul_f32_e32 v16, v35, v16
	v_mul_f32_e32 v21, v35, v21
	v_cvt_pk_bf16_f32 v22, v16, v21
	v_cvt_pk_bf16_f32 v23, v28, v23
	v_cvt_pk_bf16_f32 v24, v24, v25
	v_cvt_pk_bf16_f32 v25, v26, v27
	global_load_dwordx4 v[26:29], v[18:19], off offset:64
	ds_write_b128 v34, v[22:25] offset:1072
	ds_read_b128 v[22:25], v36 offset:128
	ds_read_b128 v[30:33], v36 offset:144
	s_waitcnt vmcnt(0)
; __device__ __forceinline__ void gmlp_item(PARAMS_T& p, int l, int b, int pos0, int tokrow0) {
;     ...
;     for (int i = 0; i < 8; ++i) {
;       u32x4 w = *reinterpret_cast<const u32x4*>(src + i * 8);
;       const int t0 = half * 64 + i * 8;
;       float f0 = __uint_as_float(w[0] << 16) * rs[t0 + 0] * gd, f1 = __uint_as_float(w[0] & 0xffff0000u) * rs[t0 + 1] * gd;
;       float f2 = __uint_as_float(w[1] << 16) * rs[t0 + 2] * gd, f3 = __uint_as_float(w[1] & 0xffff0000u) * rs[t0 + 3] * gd;
;       float f4 = __uint_as_float(w[2] << 16) * rs[t0 + 4] * gd, f5 = __uint_as_float(w[2] & 0xffff0000u) * rs[t0 + 5] * gd;
;       float f6 = __uint_as_float(w[3] << 16) * rs[t0 + 6] * gd, f7 = __uint_as_float(w[3] & 0xffff0000u) * rs[t0 + 7] * gd;
;       u32x4 o = {cvtpk(f0, f1), cvtpk(f2, f3), cvtpk(f4, f5), cvtpk(f6, f7)};
;       *reinterpret_cast<u32x4*>(Vn + dim * 136 + t0) = o;
;     }
;   }
;   __syncthreads();
	v_lshlrev_b32_e32 v16, 16, v26
	v_and_b32_e32 v21, 0xffff0000, v26
	v_lshlrev_b32_e32 v26, 16, v27
	v_and_b32_e32 v27, 0xffff0000, v27
	v_lshlrev_b32_e32 v37, 16, v28
	v_and_b32_e32 v28, 0xffff0000, v28
	v_lshlrev_b32_e32 v38, 16, v29
	v_and_b32_e32 v29, 0xffff0000, v29
	s_waitcnt lgkmcnt(1)
	v_mul_f32_e32 v16, v22, v16
	v_mul_f32_e32 v21, v23, v21
	v_mul_f32_e32 v22, v24, v26
	v_mul_f32_e32 v23, v25, v27
	s_waitcnt lgkmcnt(0)
	v_mul_f32_e32 v24, v30, v37
	v_mul_f32_e32 v25, v31, v28
	v_mul_f32_e32 v26, v32, v38
	v_mul_f32_e32 v27, v33, v29
	v_mul_f32_e32 v28, v35, v22
	v_mul_f32_e32 v23, v35, v23
	v_mul_f32_e32 v24, v35, v24
	v_mul_f32_e32 v25, v35, v25
	v_mul_f32_e32 v26, v35, v26
	v_mul_f32_e32 v27, v35, v27
	v_mul_f32_e32 v16, v35, v16
	v_mul_f32_e32 v21, v35, v21
	v_cvt_pk_bf16_f32 v22, v16, v21
	v_cvt_pk_bf16_f32 v23, v28, v23
	v_cvt_pk_bf16_f32 v24, v24, v25
	v_cvt_pk_bf16_f32 v25, v26, v27
	global_load_dwordx4 v[26:29], v[18:19], off offset:80
	ds_write_b128 v34, v[22:25] offset:1088
	ds_read_b128 v[22:25], v36 offset:160
	ds_read_b128 v[30:33], v36 offset:176
	s_waitcnt vmcnt(0)
	v_lshlrev_b32_e32 v16, 16, v26
	v_and_b32_e32 v21, 0xffff0000, v26
	v_lshlrev_b32_e32 v26, 16, v27
	v_and_b32_e32 v27, 0xffff0000, v27
	v_lshlrev_b32_e32 v37, 16, v28
	v_and_b32_e32 v28, 0xffff0000, v28
	v_lshlrev_b32_e32 v38, 16, v29
	v_and_b32_e32 v29, 0xffff0000, v29
	s_waitcnt lgkmcnt(1)
	v_mul_f32_e32 v16, v22, v16
	v_mul_f32_e32 v21, v23, v21
	v_mul_f32_e32 v22, v24, v26
	v_mul_f32_e32 v23, v25, v27
	s_waitcnt lgkmcnt(0)
	v_mul_f32_e32 v24, v30, v37
	v_mul_f32_e32 v25, v31, v28
	v_mul_f32_e32 v26, v32, v38
	v_mul_f32_e32 v27, v33, v29
	v_mul_f32_e32 v28, v35, v22
	v_mul_f32_e32 v23, v35, v23
	v_mul_f32_e32 v24, v35, v24
	v_mul_f32_e32 v25, v35, v25
	v_mul_f32_e32 v26, v35, v26
	v_mul_f32_e32 v27, v35, v27
	v_mul_f32_e32 v16, v35, v16
	v_mul_f32_e32 v21, v35, v21
	v_cvt_pk_bf16_f32 v22, v16, v21
	v_cvt_pk_bf16_f32 v23, v28, v23
	v_cvt_pk_bf16_f32 v24, v24, v25
	v_cvt_pk_bf16_f32 v25, v26, v27
	global_load_dwordx4 v[26:29], v[18:19], off offset:96
	ds_write_b128 v34, v[22:25] offset:1104
	ds_read_b128 v[22:25], v36 offset:192
	ds_read_b128 v[30:33], v36 offset:208
	s_waitcnt vmcnt(0)
	v_lshlrev_b32_e32 v16, 16, v26
	v_and_b32_e32 v21, 0xffff0000, v26
	v_lshlrev_b32_e32 v26, 16, v27
	v_and_b32_e32 v27, 0xffff0000, v27
	v_lshlrev_b32_e32 v37, 16, v28
	v_and_b32_e32 v28, 0xffff0000, v28
	v_lshlrev_b32_e32 v38, 16, v29
	v_and_b32_e32 v29, 0xffff0000, v29
	s_waitcnt lgkmcnt(1)
	v_mul_f32_e32 v16, v22, v16
	v_mul_f32_e32 v21, v23, v21
	v_mul_f32_e32 v22, v24, v26
	v_mul_f32_e32 v23, v25, v27
	s_waitcnt lgkmcnt(0)
	v_mul_f32_e32 v24, v30, v37
	v_mul_f32_e32 v25, v31, v28
	v_mul_f32_e32 v26, v32, v38
	v_mul_f32_e32 v27, v33, v29
	v_mul_f32_e32 v28, v35, v22
	v_mul_f32_e32 v23, v35, v23
	v_mul_f32_e32 v24, v35, v24
	v_mul_f32_e32 v25, v35, v25
	v_mul_f32_e32 v26, v35, v26
	v_mul_f32_e32 v27, v35, v27
	v_mul_f32_e32 v16, v35, v16
	v_mul_f32_e32 v21, v35, v21
	v_cvt_pk_bf16_f32 v22, v16, v21
	v_cvt_pk_bf16_f32 v23, v28, v23
	v_cvt_pk_bf16_f32 v24, v24, v25
	v_cvt_pk_bf16_f32 v25, v26, v27
	global_load_dwordx4 v[26:29], v[18:19], off offset:112
	v_ashrrev_i32_e32 v31, 7, v20
	v_add_u32_e32 v70, 4, v31
	v_and_b32_e32 v30, 31, v20
	v_ashrrev_i32_e32 v71, 31, v70
	v_lshlrev_b32_e32 v16, 8, v30
	v_lshlrev_b64 v[18:19], 15, v[70:71]
	v_lshl_or_b32 v78, v76, 14, v16
	v_lshl_add_u64 v[18:19], s[8:9], 0, v[18:19]
	v_lshlrev_b32_e32 v16, 4, v73
	ds_write_b128 v34, v[22:25] offset:1120
	v_lshl_add_u64 v[80:81], v[18:19], 0, v[16:17]
	ds_read_b128 v[18:21], v36 offset:224
	ds_read_b128 v[22:25], v36 offset:240
	v_lshl_add_u64 v[74:75], v[80:81], 0, v[78:79]
	v_lshl_or_b32 v72, v31, 6, v30
	v_lshlrev_b64 v[70:71], 9, v[70:71]
	s_waitcnt vmcnt(0)
	v_lshlrev_b32_e32 v32, 16, v26
	v_and_b32_e32 v26, 0xffff0000, v26
	v_lshlrev_b32_e32 v33, 16, v27
	v_and_b32_e32 v27, 0xffff0000, v27
	v_lshlrev_b32_e32 v36, 16, v28
	v_and_b32_e32 v28, 0xffff0000, v28
	v_lshlrev_b32_e32 v37, 16, v29
	v_and_b32_e32 v29, 0xffff0000, v29
	s_waitcnt lgkmcnt(1)
	v_mul_f32_e32 v18, v18, v32
	v_mul_f32_e32 v19, v19, v26
	v_mul_f32_e32 v20, v20, v33
	v_mul_f32_e32 v21, v21, v27
	s_waitcnt lgkmcnt(0)
	v_mul_f32_e32 v22, v22, v36
	v_mul_f32_e32 v23, v23, v28
	v_mul_f32_e32 v24, v24, v37
	v_mul_f32_e32 v25, v25, v29
	v_mul_f32_e32 v18, v35, v18
	v_mul_f32_e32 v19, v35, v19
	v_mul_f32_e32 v20, v35, v20
	v_mul_f32_e32 v21, v35, v21
	v_mul_f32_e32 v22, v35, v22
	v_mul_f32_e32 v23, v35, v23
	v_mul_f32_e32 v24, v35, v24
	v_mul_f32_e32 v25, v35, v25
	v_cvt_pk_bf16_f32 v18, v18, v19
	v_cvt_pk_bf16_f32 v19, v20, v21
	v_cvt_pk_bf16_f32 v20, v22, v23
	v_cvt_pk_bf16_f32 v21, v24, v25
	ds_write_b128 v34, v[18:21] offset:1136
	s_waitcnt lgkmcnt(0)
	s_barrier
; __device__ __forceinline__ void gmlp_item(PARAMS_T& p, int l, int b, int pos0, int tokrow0) {
;     ...
;   const int g = wid >> 1, th = wid & 1;
;   const bf16* wsb = (const bf16*)(p.ws + OFF_WSBF) + ((size_t)l * 4 + g) * 128 * 128;
;   f32x16 acc[2][2] = {};
; #pragma unroll
;   for (int ks = 0; ks < 8; ++ks) {
;     bf16x8 af[2], bfr[2];
; #pragma unroll
;     for (int tb = 0; tb < 2; ++tb) af[tb] = *reinterpret_cast<const bf16x8*>(wsb + (size_t)(th * 64 + tb * 32 + r32) * 128 + ks * 16 + hi * 8);
; #pragma unroll
;     for (int db = 0; db < 2; ++db) bfr[db] = *reinterpret_cast<const bf16x8*>(Vn + (g * 64 + db * 32 + r32) * 136 + ks * 16 + hi * 8);
; #pragma unroll
;     for (int tb = 0; tb < 2; ++tb)
; #pragma unroll
;       for (int db = 0; db < 2; ++db) acc[tb][db] = __builtin_amdgcn_mfma_f32_32x32x16_bf16(af[tb], bfr[db], acc[tb][db], 0, 0, 0);
;   }
	v_and_b32_e32 v250, 31, v192
	v_bfe_u32 v251, v192, 5, 1
	v_lshrrev_b32_e32 v252, 7, v192
	v_bfe_u32 v253, v192, 6, 1
	v_lshl_or_b32 v254, v252, 6, v250
	v_lshlrev_b32_e32 v172, 1, v254
	v_mul_u32_u24_e32 v254, 0x110, v254
	v_lshl_add_u32 v254, v251, 4, v254
	v_add_u32_e32 v16, 0x400, v254
	v_add_u32_e32 v252, 4, v252
	v_lshl_or_b32 v254, v253, 6, v250
	v_lshlrev_b32_e32 v254, 8, v254
	v_lshl_or_b32 v254, v251, 4, v254
	v_lshl_add_u32 v254, v252, 15, v254
	v_mov_b32_e32 v162, v254
	v_mov_b32_e32 v163, 0
	v_lshl_add_u64 v[162:163], s[8:9], 0, v[162:163]
	v_mov_b32_e32 v164, 0x2000
	v_mov_b32_e32 v165, 0
	v_lshl_add_u64 v[164:165], v[162:163], 0, v[164:165]
	global_load_dwordx4 v[82:85], v[162:163], off
	global_load_dwordx4 v[86:89], v[164:165], off
	global_load_dwordx4 v[90:93], v[162:163], off offset:32
	global_load_dwordx4 v[94:97], v[164:165], off offset:32
	global_load_dwordx4 v[98:101], v[162:163], off offset:64
	global_load_dwordx4 v[102:105], v[164:165], off offset:64
	global_load_dwordx4 v[106:109], v[162:163], off offset:96
	global_load_dwordx4 v[110:113], v[164:165], off offset:96
	global_load_dwordx4 v[114:117], v[162:163], off offset:128
	global_load_dwordx4 v[118:121], v[164:165], off offset:128
	global_load_dwordx4 v[122:125], v[162:163], off offset:160
	global_load_dwordx4 v[126:129], v[164:165], off offset:160
	global_load_dwordx4 v[130:133], v[162:163], off offset:192
	global_load_dwordx4 v[134:137], v[164:165], off offset:192
	global_load_dwordx4 v[138:141], v[162:163], off offset:224
	global_load_dwordx4 v[142:145], v[164:165], off offset:224
	v_lshlrev_b32_e32 v171, 6, v253
	v_lshl_add_u32 v171, v251, 2, v171
	v_lshl_add_u32 v170, v252, 7, v171
	v_lshlrev_b32_e32 v170, 2, v170
	v_add_u32_e32 v171, s3, v171
	v_add_u32_e32 v254, 0, v171
	v_lshl_add_u32 v162, v254, 9, v172
	v_add_u32_e32 v254, 8, v171
	v_lshl_add_u32 v163, v254, 9, v172
	v_add_u32_e32 v254, 16, v171
	v_lshl_add_u32 v164, v254, 9, v172
	v_add_u32_e32 v254, 24, v171
	v_lshl_add_u32 v165, v254, 9, v172
	v_add_u32_e32 v254, 32, v171
	v_lshl_add_u32 v166, v254, 9, v172
	v_add_u32_e32 v254, 40, v171
	v_lshl_add_u32 v167, v254, 9, v172
	v_add_u32_e32 v254, 48, v171
	v_lshl_add_u32 v168, v254, 9, v172
	v_add_u32_e32 v254, 56, v171
	v_lshl_add_u32 v169, v254, 9, v172
	v_mov_b32_e32 v18, 0
	v_mov_b32_e32 v19, 0
	v_mov_b32_e32 v20, 0
	v_mov_b32_e32 v21, 0
	v_mov_b32_e32 v22, 0
	v_mov_b32_e32 v23, 0
	v_mov_b32_e32 v24, 0
	v_mov_b32_e32 v25, 0
	v_mov_b32_e32 v26, 0
	v_mov_b32_e32 v27, 0
	v_mov_b32_e32 v28, 0
	v_mov_b32_e32 v29, 0
	v_mov_b32_e32 v30, 0
	v_mov_b32_e32 v31, 0
	v_mov_b32_e32 v32, 0
	v_mov_b32_e32 v33, 0
	v_mov_b32_e32 v34, 0
	v_mov_b32_e32 v35, 0
	v_mov_b32_e32 v36, 0
	v_mov_b32_e32 v37, 0
	v_mov_b32_e32 v38, 0
	v_mov_b32_e32 v39, 0
	v_mov_b32_e32 v40, 0
	v_mov_b32_e32 v41, 0
	v_mov_b32_e32 v42, 0
	v_mov_b32_e32 v43, 0
	v_mov_b32_e32 v44, 0
	v_mov_b32_e32 v45, 0
	v_mov_b32_e32 v46, 0
	v_mov_b32_e32 v47, 0
	v_mov_b32_e32 v48, 0
	v_mov_b32_e32 v49, 0
	v_mov_b32_e32 v50, 0
	v_mov_b32_e32 v51, 0
	v_mov_b32_e32 v52, 0
	v_mov_b32_e32 v53, 0
	v_mov_b32_e32 v54, 0
	v_mov_b32_e32 v55, 0
	v_mov_b32_e32 v56, 0
	v_mov_b32_e32 v57, 0
	v_mov_b32_e32 v58, 0
	v_mov_b32_e32 v59, 0
	v_mov_b32_e32 v60, 0
	v_mov_b32_e32 v61, 0
	v_mov_b32_e32 v62, 0
	v_mov_b32_e32 v63, 0
	v_mov_b32_e32 v64, 0
	v_mov_b32_e32 v65, 0
	v_mov_b32_e32 v66, 0
	v_mov_b32_e32 v67, 0
	v_mov_b32_e32 v68, 0
	v_mov_b32_e32 v69, 0
	v_mov_b32_e32 v70, 0
	v_mov_b32_e32 v71, 0
	v_mov_b32_e32 v72, 0
	v_mov_b32_e32 v73, 0
	v_mov_b32_e32 v74, 0
	v_mov_b32_e32 v75, 0
	v_mov_b32_e32 v76, 0
	v_mov_b32_e32 v77, 0
	v_mov_b32_e32 v78, 0
	v_mov_b32_e32 v79, 0
	v_mov_b32_e32 v80, 0
	v_mov_b32_e32 v81, 0
	ds_read_b128 v[146:149], v16 offset:0
	ds_read_b128 v[150:153], v16 offset:8704
	ds_read_b128 v[154:157], v16 offset:32
	ds_read_b128 v[158:161], v16 offset:8736
	ds_read_b128 v[234:237], v16 offset:64
	ds_read_b128 v[238:241], v16 offset:8768
	ds_read_b128 v[242:245], v16 offset:96
	ds_read_b128 v[246:249], v16 offset:8800
	s_waitcnt vmcnt(15) lgkmcnt(7)
	v_mfma_f32_32x32x16_bf16 v[18:33], v[82:85], v[146:149], v[18:33]
	s_waitcnt vmcnt(15) lgkmcnt(6)
	v_mfma_f32_32x32x16_bf16 v[34:49], v[82:85], v[150:153], v[34:49]
	s_waitcnt vmcnt(14)
	v_mfma_f32_32x32x16_bf16 v[50:65], v[86:89], v[146:149], v[50:65]
	v_mfma_f32_32x32x16_bf16 v[66:81], v[86:89], v[150:153], v[66:81]
	s_waitcnt vmcnt(13) lgkmcnt(5)
	v_mfma_f32_32x32x16_bf16 v[18:33], v[90:93], v[154:157], v[18:33]
	s_waitcnt vmcnt(13) lgkmcnt(4)
	v_mfma_f32_32x32x16_bf16 v[34:49], v[90:93], v[158:161], v[34:49]
	s_waitcnt vmcnt(12)
	v_mfma_f32_32x32x16_bf16 v[50:65], v[94:97], v[154:157], v[50:65]
	v_mfma_f32_32x32x16_bf16 v[66:81], v[94:97], v[158:161], v[66:81]
	s_waitcnt vmcnt(11) lgkmcnt(3)
	v_mfma_f32_32x32x16_bf16 v[18:33], v[98:101], v[234:237], v[18:33]
	s_waitcnt vmcnt(11) lgkmcnt(2)
	v_mfma_f32_32x32x16_bf16 v[34:49], v[98:101], v[238:241], v[34:49]
	s_waitcnt vmcnt(10)
	v_mfma_f32_32x32x16_bf16 v[50:65], v[102:105], v[234:237], v[50:65]
	v_mfma_f32_32x32x16_bf16 v[66:81], v[102:105], v[238:241], v[66:81]
	s_waitcnt vmcnt(9) lgkmcnt(1)
	v_mfma_f32_32x32x16_bf16 v[18:33], v[106:109], v[242:245], v[18:33]
	s_waitcnt vmcnt(9) lgkmcnt(0)
	v_mfma_f32_32x32x16_bf16 v[34:49], v[106:109], v[246:249], v[34:49]
	s_waitcnt vmcnt(8)
	v_mfma_f32_32x32x16_bf16 v[50:65], v[110:113], v[242:245], v[50:65]
	v_mfma_f32_32x32x16_bf16 v[66:81], v[110:113], v[246:249], v[66:81]
	ds_read_b128 v[146:149], v16 offset:128
	ds_read_b128 v[150:153], v16 offset:8832
	ds_read_b128 v[154:157], v16 offset:160
	ds_read_b128 v[158:161], v16 offset:8864
	ds_read_b128 v[234:237], v16 offset:192
	ds_read_b128 v[238:241], v16 offset:8896
	ds_read_b128 v[242:245], v16 offset:224
	ds_read_b128 v[246:249], v16 offset:8928
	s_waitcnt vmcnt(7) lgkmcnt(7)
; __device__ __forceinline__ unsigned short bf1(float a) { return (unsigned short)(cvtpk(a, 0.f) & 0xffffu); }
; __device__ __forceinline__ int crow(int r, int hi) { return (r & 3) + 8 * (r >> 2) + 4 * hi; }
; __device__ __forceinline__ void gmlp_item(PARAMS_T& p, int l, int b, int pos0, int tokrow0) {
;     ...
; #pragma unroll
;   for (int ks = 0; ks < 8; ++ks) {
;     bf16x8 af[2], bfr[2];
; #pragma unroll
;     for (int tb = 0; tb < 2; ++tb) af[tb] = *reinterpret_cast<const bf16x8*>(wsb + (size_t)(th * 64 + tb * 32 + r32) * 128 + ks * 16 + hi * 8);
; #pragma unroll
;     for (int db = 0; db < 2; ++db) bfr[db] = *reinterpret_cast<const bf16x8*>(Vn + (g * 64 + db * 32 + r32) * 136 + ks * 16 + hi * 8);
; #pragma unroll
;     for (int tb = 0; tb < 2; ++tb)
; #pragma unroll
;       for (int db = 0; db < 2; ++db) acc[tb][db] = __builtin_amdgcn_mfma_f32_32x32x16_bf16(af[tb], bfr[db], acc[tb][db], 0, 0, 0);
;   }
;   const float* bs = p.gm_bs + ((size_t)l * 4 + g) * 128;
;   const unsigned short* u = (const unsigned short*)(p.ws + OFF_U);
;   unsigned short* outp = (unsigned short*)(p.ws + OFF_ACTA);
; #pragma unroll
;   for (int tb = 0; tb < 2; ++tb)
; #pragma unroll
;     for (int r = 0; r < 16; ++r) {
;       const int t = th * 64 + tb * 32 + crow(r, hi);
;       const float bt = bs[t];
; #pragma unroll
;       for (int db = 0; db < 2; ++db) {
;         const int d = g * 64 + db * 32 + r32;
;         const float uv = __uint_as_float(((unsigned)u[(size_t)(tokrow0 + t) * 256 + d]) << 16);
;         outp[(size_t)(tokrow0 + t) * 1024 + 256 + d] = bf1(uv * (acc[tb][db][r] + bt));
;       }
;     }
	v_mfma_f32_32x32x16_bf16 v[18:33], v[114:117], v[146:149], v[18:33]
	s_waitcnt vmcnt(7) lgkmcnt(6)
	v_mfma_f32_32x32x16_bf16 v[34:49], v[114:117], v[150:153], v[34:49]
	s_waitcnt vmcnt(6)
	v_mfma_f32_32x32x16_bf16 v[50:65], v[118:121], v[146:149], v[50:65]
	v_mfma_f32_32x32x16_bf16 v[66:81], v[118:121], v[150:153], v[66:81]
	s_waitcnt vmcnt(5) lgkmcnt(5)
	v_mfma_f32_32x32x16_bf16 v[18:33], v[122:125], v[154:157], v[18:33]
	s_waitcnt vmcnt(5) lgkmcnt(4)
	v_mfma_f32_32x32x16_bf16 v[34:49], v[122:125], v[158:161], v[34:49]
	s_waitcnt vmcnt(4)
	v_mfma_f32_32x32x16_bf16 v[50:65], v[126:129], v[154:157], v[50:65]
	v_mfma_f32_32x32x16_bf16 v[66:81], v[126:129], v[158:161], v[66:81]
	s_waitcnt vmcnt(3) lgkmcnt(3)
	v_mfma_f32_32x32x16_bf16 v[18:33], v[130:133], v[234:237], v[18:33]
	s_waitcnt vmcnt(3) lgkmcnt(2)
	v_mfma_f32_32x32x16_bf16 v[34:49], v[130:133], v[238:241], v[34:49]
	s_waitcnt vmcnt(2)
	v_mfma_f32_32x32x16_bf16 v[50:65], v[134:137], v[234:237], v[50:65]
	v_mfma_f32_32x32x16_bf16 v[66:81], v[134:137], v[238:241], v[66:81]
	s_waitcnt vmcnt(1) lgkmcnt(1)
	v_mfma_f32_32x32x16_bf16 v[18:33], v[138:141], v[242:245], v[18:33]
	s_waitcnt vmcnt(1) lgkmcnt(0)
	v_mfma_f32_32x32x16_bf16 v[34:49], v[138:141], v[246:249], v[34:49]
	s_waitcnt vmcnt(0)
	v_mfma_f32_32x32x16_bf16 v[50:65], v[142:145], v[242:245], v[50:65]
	v_mfma_f32_32x32x16_bf16 v[66:81], v[142:145], v[246:249], v[66:81]
	v_bfe_u32 v250, v192, 3, 3
	v_and_b32_e32 v251, 7, v192
	v_bfe_u32 v253, v192, 6, 1
	v_lshrrev_b32_e32 v254, 7, v192
	v_lshl_add_u32 v167, v253, 6, v250
	v_lshl_add_u32 v166, v254, 7, v167
	v_add_u32_e32 v166, 512, v166
	v_lshlrev_b32_e32 v166, 2, v166
	v_add_u32_e32 v167, s3, v167
	v_lshlrev_b32_e32 v168, 7, v254
	v_lshl_add_u32 v168, v251, 4, v168
	v_lshl_add_u32 v164, v167, 9, v168
	v_lshl_add_u32 v165, v167, 11, v168
	v_add_u32_e32 v167, 0x0, v164
	global_load_dwordx4 v[82:85], v167, s[94:95]
	v_add_u32_e32 v168, 0x1000, v164
	global_load_dwordx4 v[86:89], v168, s[94:95]
	v_add_u32_e32 v167, 0x2000, v164
	global_load_dwordx4 v[90:93], v167, s[94:95]
	v_add_u32_e32 v168, 0x3000, v164
	global_load_dwordx4 v[94:97], v168, s[94:95]
	v_add_u32_e32 v167, 0x4000, v164
	global_load_dwordx4 v[98:101], v167, s[94:95]
	v_add_u32_e32 v168, 0x5000, v164
	global_load_dwordx4 v[102:105], v168, s[94:95]
	v_add_u32_e32 v167, 0x6000, v164
	global_load_dwordx4 v[106:109], v167, s[94:95]
	v_add_u32_e32 v168, 0x7000, v164
	global_load_dwordx4 v[110:113], v168, s[94:95]
	global_load_dword v114, v166, s[6:7]
	global_load_dword v115, v166, s[6:7] offset:32
	global_load_dword v116, v166, s[6:7] offset:64
	global_load_dword v117, v166, s[6:7] offset:96
	global_load_dword v118, v166, s[6:7] offset:128
	global_load_dword v119, v166, s[6:7] offset:160
	global_load_dword v120, v166, s[6:7] offset:192
	global_load_dword v121, v166, s[6:7] offset:224
	v_lshrrev_b32_e32 v253, 6, v192
	v_mul_u32_u24_e32 v253, 0x1100, v253
	v_add_u32_e32 v253, 0x11800, v253
	v_mul_u32_u24_e32 v163, 0x110, v250
	v_lshl_add_u32 v163, v251, 5, v163
	v_add_u32_e32 v163, v253, v163
	v_and_b32_e32 v250, 31, v192
	v_bfe_u32 v251, v192, 5, 1
	v_mul_u32_u24_e32 v162, 0x440, v251
	v_lshl_add_u32 v162, v250, 2, v162
	v_add_u32_e32 v162, v253, v162
	ds_write_b32 v162, v18
	ds_write_b32 v162, v34 offset:128
	ds_write_b32 v162, v19 offset:272
	ds_write_b32 v162, v35 offset:400
	ds_write_b32 v162, v20 offset:544
	ds_write_b32 v162, v36 offset:672
	ds_write_b32 v162, v21 offset:816
	ds_write_b32 v162, v37 offset:944
	ds_write_b32 v162, v22 offset:2176
	ds_write_b32 v162, v38 offset:2304
	ds_write_b32 v162, v23 offset:2448
	ds_write_b32 v162, v39 offset:2576
	ds_write_b32 v162, v24 offset:2720
	ds_write_b32 v162, v40 offset:2848
	ds_write_b32 v162, v25 offset:2992
	ds_write_b32 v162, v41 offset:3120
	ds_read_b128 v[122:125], v163 offset:0
	ds_read_b128 v[126:129], v163 offset:16
	ds_read_b128 v[130:133], v163 offset:2176
	ds_read_b128 v[134:137], v163 offset:2192
	s_waitcnt vmcnt(0)
	s_waitcnt lgkmcnt(2)
	v_add_f32_e32 v252, v122, v114
	v_lshlrev_b32_e32 v253, 16, v82
	v_mul_f32_e32 v250, v252, v253
	v_add_f32_e32 v252, v123, v114
	v_and_b32_e32 v253, 0xffff0000, v82
	v_mul_f32_e32 v251, v252, v253
	v_cvt_pk_bf16_f32 v154, v250, v251
	v_add_f32_e32 v252, v124, v114
	v_lshlrev_b32_e32 v253, 16, v83
	v_mul_f32_e32 v250, v252, v253
	v_add_f32_e32 v252, v125, v114
	v_and_b32_e32 v253, 0xffff0000, v83
	v_mul_f32_e32 v251, v252, v253
	v_cvt_pk_bf16_f32 v155, v250, v251
	v_add_f32_e32 v252, v126, v114
	v_lshlrev_b32_e32 v253, 16, v84
	v_mul_f32_e32 v250, v252, v253
	v_add_f32_e32 v252, v127, v114
	v_and_b32_e32 v253, 0xffff0000, v84
	v_mul_f32_e32 v251, v252, v253
	v_cvt_pk_bf16_f32 v156, v250, v251
	v_add_f32_e32 v252, v128, v114
	v_lshlrev_b32_e32 v253, 16, v85
	v_mul_f32_e32 v250, v252, v253
	v_add_f32_e32 v252, v129, v114
	v_and_b32_e32 v253, 0xffff0000, v85
	v_mul_f32_e32 v251, v252, v253
	v_cvt_pk_bf16_f32 v157, v250, v251
	v_add_u32_e32 v167, 0x0, v165
	global_store_dwordx4 v167, v[154:157], s[96:97]
	s_waitcnt lgkmcnt(0)
; __device__ __forceinline__ unsigned short bf1(float a) { return (unsigned short)(cvtpk(a, 0.f) & 0xffffu); }
; __device__ __forceinline__ int crow(int r, int hi) { return (r & 3) + 8 * (r >> 2) + 4 * hi; }
; __device__ __forceinline__ void gmlp_item(PARAMS_T& p, int l, int b, int pos0, int tokrow0) {
;     ...
; #pragma unroll
;   for (int tb = 0; tb < 2; ++tb)
; #pragma unroll
;     for (int r = 0; r < 16; ++r) {
;       const int t = th * 64 + tb * 32 + crow(r, hi);
;       const float bt = bs[t];
; #pragma unroll
;       for (int db = 0; db < 2; ++db) {
;         const int d = g * 64 + db * 32 + r32;
;         const float uv = __uint_as_float(((unsigned)u[(size_t)(tokrow0 + t) * 256 + d]) << 16);
;         outp[(size_t)(tokrow0 + t) * 1024 + 256 + d] = bf1(uv * (acc[tb][db][r] + bt));
;       }
;     }
	v_add_f32_e32 v252, v130, v115
	v_lshlrev_b32_e32 v253, 16, v86
	v_mul_f32_e32 v250, v252, v253
	v_add_f32_e32 v252, v131, v115
	v_and_b32_e32 v253, 0xffff0000, v86
	v_mul_f32_e32 v251, v252, v253
	v_cvt_pk_bf16_f32 v158, v250, v251
	v_add_f32_e32 v252, v132, v115
	v_lshlrev_b32_e32 v253, 16, v87
	v_mul_f32_e32 v250, v252, v253
	v_add_f32_e32 v252, v133, v115
	v_and_b32_e32 v253, 0xffff0000, v87
	v_mul_f32_e32 v251, v252, v253
	v_cvt_pk_bf16_f32 v159, v250, v251
	v_add_f32_e32 v252, v134, v115
	v_lshlrev_b32_e32 v253, 16, v88
	v_mul_f32_e32 v250, v252, v253
	v_add_f32_e32 v252, v135, v115
	v_and_b32_e32 v253, 0xffff0000, v88
	v_mul_f32_e32 v251, v252, v253
	v_cvt_pk_bf16_f32 v160, v250, v251
	v_add_f32_e32 v252, v136, v115
	v_lshlrev_b32_e32 v253, 16, v89
	v_mul_f32_e32 v250, v252, v253
	v_add_f32_e32 v252, v137, v115
	v_and_b32_e32 v253, 0xffff0000, v89
	v_mul_f32_e32 v251, v252, v253
	v_cvt_pk_bf16_f32 v161, v250, v251
	v_add_u32_e32 v168, 0x4000, v165
	global_store_dwordx4 v168, v[158:161], s[96:97]
	ds_write_b32 v162, v26
	ds_write_b32 v162, v42 offset:128
	ds_write_b32 v162, v27 offset:272
	ds_write_b32 v162, v43 offset:400
	ds_write_b32 v162, v28 offset:544
	ds_write_b32 v162, v44 offset:672
	ds_write_b32 v162, v29 offset:816
	ds_write_b32 v162, v45 offset:944
	ds_write_b32 v162, v30 offset:2176
	ds_write_b32 v162, v46 offset:2304
	ds_write_b32 v162, v31 offset:2448
	ds_write_b32 v162, v47 offset:2576
	ds_write_b32 v162, v32 offset:2720
	ds_write_b32 v162, v48 offset:2848
	ds_write_b32 v162, v33 offset:2992
	ds_write_b32 v162, v49 offset:3120
	ds_read_b128 v[122:125], v163 offset:0
	ds_read_b128 v[126:129], v163 offset:16
	ds_read_b128 v[130:133], v163 offset:2176
	ds_read_b128 v[134:137], v163 offset:2192
	s_waitcnt lgkmcnt(2)
	v_add_f32_e32 v252, v122, v116
	v_lshlrev_b32_e32 v253, 16, v90
	v_mul_f32_e32 v250, v252, v253
	v_add_f32_e32 v252, v123, v116
	v_and_b32_e32 v253, 0xffff0000, v90
	v_mul_f32_e32 v251, v252, v253
	v_cvt_pk_bf16_f32 v154, v250, v251
	v_add_f32_e32 v252, v124, v116
	v_lshlrev_b32_e32 v253, 16, v91
	v_mul_f32_e32 v250, v252, v253
	v_add_f32_e32 v252, v125, v116
	v_and_b32_e32 v253, 0xffff0000, v91
	v_mul_f32_e32 v251, v252, v253
	v_cvt_pk_bf16_f32 v155, v250, v251
	v_add_f32_e32 v252, v126, v116
	v_lshlrev_b32_e32 v253, 16, v92
	v_mul_f32_e32 v250, v252, v253
	v_add_f32_e32 v252, v127, v116
	v_and_b32_e32 v253, 0xffff0000, v92
	v_mul_f32_e32 v251, v252, v253
	v_cvt_pk_bf16_f32 v156, v250, v251
	v_add_f32_e32 v252, v128, v116
	v_lshlrev_b32_e32 v253, 16, v93
	v_mul_f32_e32 v250, v252, v253
	v_add_f32_e32 v252, v129, v116
	v_and_b32_e32 v253, 0xffff0000, v93
	v_mul_f32_e32 v251, v252, v253
	v_cvt_pk_bf16_f32 v157, v250, v251
	v_add_u32_e32 v167, 0x8000, v165
	global_store_dwordx4 v167, v[154:157], s[96:97]
	s_waitcnt lgkmcnt(0)
	v_add_f32_e32 v252, v130, v117
	v_lshlrev_b32_e32 v253, 16, v94
	v_mul_f32_e32 v250, v252, v253
	v_add_f32_e32 v252, v131, v117
	v_and_b32_e32 v253, 0xffff0000, v94
	v_mul_f32_e32 v251, v252, v253
	v_cvt_pk_bf16_f32 v158, v250, v251
	v_add_f32_e32 v252, v132, v117
	v_lshlrev_b32_e32 v253, 16, v95
	v_mul_f32_e32 v250, v252, v253
	v_add_f32_e32 v252, v133, v117
	v_and_b32_e32 v253, 0xffff0000, v95
	v_mul_f32_e32 v251, v252, v253
	v_cvt_pk_bf16_f32 v159, v250, v251
	v_add_f32_e32 v252, v134, v117
	v_lshlrev_b32_e32 v253, 16, v96
	v_mul_f32_e32 v250, v252, v253
	v_add_f32_e32 v252, v135, v117
	v_and_b32_e32 v253, 0xffff0000, v96
	v_mul_f32_e32 v251, v252, v253
	v_cvt_pk_bf16_f32 v160, v250, v251
	v_add_f32_e32 v252, v136, v117
	v_lshlrev_b32_e32 v253, 16, v97
	v_mul_f32_e32 v250, v252, v253
	v_add_f32_e32 v252, v137, v117
	v_and_b32_e32 v253, 0xffff0000, v97
	v_mul_f32_e32 v251, v252, v253
	v_cvt_pk_bf16_f32 v161, v250, v251
	v_add_u32_e32 v168, 0xc000, v165
	global_store_dwordx4 v168, v[158:161], s[96:97]
	ds_write_b32 v162, v50
	ds_write_b32 v162, v66 offset:128
	ds_write_b32 v162, v51 offset:272
	ds_write_b32 v162, v67 offset:400
	ds_write_b32 v162, v52 offset:544
	ds_write_b32 v162, v68 offset:672
	ds_write_b32 v162, v53 offset:816
	ds_write_b32 v162, v69 offset:944
	ds_write_b32 v162, v54 offset:2176
	ds_write_b32 v162, v70 offset:2304
	ds_write_b32 v162, v55 offset:2448
	ds_write_b32 v162, v71 offset:2576
	ds_write_b32 v162, v56 offset:2720
	ds_write_b32 v162, v72 offset:2848
	ds_write_b32 v162, v57 offset:2992
	ds_write_b32 v162, v73 offset:3120
	ds_read_b128 v[122:125], v163 offset:0
	ds_read_b128 v[126:129], v163 offset:16
	ds_read_b128 v[130:133], v163 offset:2176
	ds_read_b128 v[134:137], v163 offset:2192
	s_waitcnt lgkmcnt(2)
; __device__ __forceinline__ unsigned short bf1(float a) { return (unsigned short)(cvtpk(a, 0.f) & 0xffffu); }
; __device__ __forceinline__ int crow(int r, int hi) { return (r & 3) + 8 * (r >> 2) + 4 * hi; }
; __device__ __forceinline__ void gmlp_item(PARAMS_T& p, int l, int b, int pos0, int tokrow0) {
;     ...
; #pragma unroll
;   for (int tb = 0; tb < 2; ++tb)
; #pragma unroll
;     for (int r = 0; r < 16; ++r) {
;       const int t = th * 64 + tb * 32 + crow(r, hi);
;       const float bt = bs[t];
; #pragma unroll
;       for (int db = 0; db < 2; ++db) {
;         const int d = g * 64 + db * 32 + r32;
;         const float uv = __uint_as_float(((unsigned)u[(size_t)(tokrow0 + t) * 256 + d]) << 16);
;         outp[(size_t)(tokrow0 + t) * 1024 + 256 + d] = bf1(uv * (acc[tb][db][r] + bt));
;       }
;     }
	v_add_f32_e32 v252, v122, v118
	v_lshlrev_b32_e32 v253, 16, v98
	v_mul_f32_e32 v250, v252, v253
	v_add_f32_e32 v252, v123, v118
	v_and_b32_e32 v253, 0xffff0000, v98
	v_mul_f32_e32 v251, v252, v253
	v_cvt_pk_bf16_f32 v154, v250, v251
	v_add_f32_e32 v252, v124, v118
	v_lshlrev_b32_e32 v253, 16, v99
	v_mul_f32_e32 v250, v252, v253
	v_add_f32_e32 v252, v125, v118
	v_and_b32_e32 v253, 0xffff0000, v99
	v_mul_f32_e32 v251, v252, v253
	v_cvt_pk_bf16_f32 v155, v250, v251
	v_add_f32_e32 v252, v126, v118
	v_lshlrev_b32_e32 v253, 16, v100
	v_mul_f32_e32 v250, v252, v253
	v_add_f32_e32 v252, v127, v118
	v_and_b32_e32 v253, 0xffff0000, v100
	v_mul_f32_e32 v251, v252, v253
	v_cvt_pk_bf16_f32 v156, v250, v251
	v_add_f32_e32 v252, v128, v118
	v_lshlrev_b32_e32 v253, 16, v101
	v_mul_f32_e32 v250, v252, v253
	v_add_f32_e32 v252, v129, v118
	v_and_b32_e32 v253, 0xffff0000, v101
	v_mul_f32_e32 v251, v252, v253
	v_cvt_pk_bf16_f32 v157, v250, v251
	v_add_u32_e32 v167, 0x10000, v165
	global_store_dwordx4 v167, v[154:157], s[96:97]
	s_waitcnt lgkmcnt(0)
	v_add_f32_e32 v252, v130, v119
	v_lshlrev_b32_e32 v253, 16, v102
	v_mul_f32_e32 v250, v252, v253
	v_add_f32_e32 v252, v131, v119
	v_and_b32_e32 v253, 0xffff0000, v102
	v_mul_f32_e32 v251, v252, v253
	v_cvt_pk_bf16_f32 v158, v250, v251
	v_add_f32_e32 v252, v132, v119
	v_lshlrev_b32_e32 v253, 16, v103
	v_mul_f32_e32 v250, v252, v253
	v_add_f32_e32 v252, v133, v119
	v_and_b32_e32 v253, 0xffff0000, v103
	v_mul_f32_e32 v251, v252, v253
	v_cvt_pk_bf16_f32 v159, v250, v251
	v_add_f32_e32 v252, v134, v119
	v_lshlrev_b32_e32 v253, 16, v104
	v_mul_f32_e32 v250, v252, v253
	v_add_f32_e32 v252, v135, v119
	v_and_b32_e32 v253, 0xffff0000, v104
	v_mul_f32_e32 v251, v252, v253
	v_cvt_pk_bf16_f32 v160, v250, v251
	v_add_f32_e32 v252, v136, v119
	v_lshlrev_b32_e32 v253, 16, v105
	v_mul_f32_e32 v250, v252, v253
	v_add_f32_e32 v252, v137, v119
	v_and_b32_e32 v253, 0xffff0000, v105
	v_mul_f32_e32 v251, v252, v253
	v_cvt_pk_bf16_f32 v161, v250, v251
	v_add_u32_e32 v168, 0x14000, v165
	global_store_dwordx4 v168, v[158:161], s[96:97]
	ds_write_b32 v162, v58
	ds_write_b32 v162, v74 offset:128
	ds_write_b32 v162, v59 offset:272
	ds_write_b32 v162, v75 offset:400
	ds_write_b32 v162, v60 offset:544
	ds_write_b32 v162, v76 offset:672
	ds_write_b32 v162, v61 offset:816
	ds_write_b32 v162, v77 offset:944
	ds_write_b32 v162, v62 offset:2176
	ds_write_b32 v162, v78 offset:2304
	ds_write_b32 v162, v63 offset:2448
	ds_write_b32 v162, v79 offset:2576
	ds_write_b32 v162, v64 offset:2720
	ds_write_b32 v162, v80 offset:2848
	ds_write_b32 v162, v65 offset:2992
	ds_write_b32 v162, v81 offset:3120
	ds_read_b128 v[122:125], v163 offset:0
	ds_read_b128 v[126:129], v163 offset:16
	ds_read_b128 v[130:133], v163 offset:2176
	ds_read_b128 v[134:137], v163 offset:2192
	s_waitcnt lgkmcnt(2)
	v_add_f32_e32 v252, v122, v120
	v_lshlrev_b32_e32 v253, 16, v106
	v_mul_f32_e32 v250, v252, v253
	v_add_f32_e32 v252, v123, v120
	v_and_b32_e32 v253, 0xffff0000, v106
	v_mul_f32_e32 v251, v252, v253
	v_cvt_pk_bf16_f32 v154, v250, v251
	v_add_f32_e32 v252, v124, v120
	v_lshlrev_b32_e32 v253, 16, v107
	v_mul_f32_e32 v250, v252, v253
	v_add_f32_e32 v252, v125, v120
	v_and_b32_e32 v253, 0xffff0000, v107
	v_mul_f32_e32 v251, v252, v253
	v_cvt_pk_bf16_f32 v155, v250, v251
	v_add_f32_e32 v252, v126, v120
	v_lshlrev_b32_e32 v253, 16, v108
	v_mul_f32_e32 v250, v252, v253
	v_add_f32_e32 v252, v127, v120
	v_and_b32_e32 v253, 0xffff0000, v108
	v_mul_f32_e32 v251, v252, v253
	v_cvt_pk_bf16_f32 v156, v250, v251
	v_add_f32_e32 v252, v128, v120
	v_lshlrev_b32_e32 v253, 16, v109
	v_mul_f32_e32 v250, v252, v253
	v_add_f32_e32 v252, v129, v120
	v_and_b32_e32 v253, 0xffff0000, v109
	v_mul_f32_e32 v251, v252, v253
	v_cvt_pk_bf16_f32 v157, v250, v251
	v_add_u32_e32 v167, 0x18000, v165
	global_store_dwordx4 v167, v[154:157], s[96:97]
	s_waitcnt lgkmcnt(0)
	v_add_f32_e32 v252, v130, v121
	v_lshlrev_b32_e32 v253, 16, v110
	v_mul_f32_e32 v250, v252, v253
	v_add_f32_e32 v252, v131, v121
	v_and_b32_e32 v253, 0xffff0000, v110
	v_mul_f32_e32 v251, v252, v253
	v_cvt_pk_bf16_f32 v158, v250, v251
	v_add_f32_e32 v252, v132, v121
	v_lshlrev_b32_e32 v253, 16, v111
	v_mul_f32_e32 v250, v252, v253
	v_add_f32_e32 v252, v133, v121
	v_and_b32_e32 v253, 0xffff0000, v111
	v_mul_f32_e32 v251, v252, v253
	v_cvt_pk_bf16_f32 v159, v250, v251
	v_add_f32_e32 v252, v134, v121
	v_lshlrev_b32_e32 v253, 16, v112
	v_mul_f32_e32 v250, v252, v253
	v_add_f32_e32 v252, v135, v121
	v_and_b32_e32 v253, 0xffff0000, v112
	v_mul_f32_e32 v251, v252, v253
	v_cvt_pk_bf16_f32 v160, v250, v251
	v_add_f32_e32 v252, v136, v121
	v_lshlrev_b32_e32 v253, 16, v113
	v_mul_f32_e32 v250, v252, v253
	v_add_f32_e32 v252, v137, v121
	v_and_b32_e32 v253, 0xffff0000, v113
	v_mul_f32_e32 v251, v252, v253
	v_cvt_pk_bf16_f32 v161, v250, v251
	v_add_u32_e32 v168, 0x1c000, v165
	global_store_dwordx4 v168, v[158:161], s[96:97]
	s_mov_b64 s[6:7], 0
